# first K-iteration peeled with zero SrcC on first-touch MFMAs; per-tile accumulator clears removed; far-branch trampoline
# speedup vs baseline: 1.0062x; 1.0010x over previous
.LBB0_46:
	s_ashr_i32 s49, s48, 31
	s_lshl_b64 s[22:23], s[48:49], 19
	v_cmp_lt_i64_e32 vcc, s[52:53], v[164:165]
	s_add_u32 s52, s96, s22
	s_addc_u32 s53, s97, s23
	s_and_b64 s[22:23], vcc, exec
	s_cselect_b32 s21, s53, s29
	s_cselect_b32 s34, s52, s28
	s_ashr_i32 s47, s46, 31
	s_lshl_b64 s[22:23], s[46:47], 19
	s_add_u32 s54, s16, s22
	s_addc_u32 s55, s17, s23
	s_and_b64 s[22:23], vcc, exec
	s_cselect_b32 s47, s55, s31
	s_cselect_b32 s49, s54, s30
	s_add_u32 s28, s28, 0x40080
	s_addc_u32 s29, s29, 0
	s_add_u32 s67, s30, 0x100
	s_addc_u32 s68, s31, 0
	s_mov_b32 s69, -2
	s_waitcnt lgkmcnt(0)
	s_cmpk_gt_u32 s0, 0xff
	s_cbranch_scc0 .Lrs_i1_pre
	s_barrier
.Lrs_i1_pre:
	s_add_u32 s1, s28, 0xfffc0080
	s_addc_u32 s22, s29, -1
	s_add_i32 s23, 0, 0x10000
	v_add_u32_e32 v142, s23, v195
	ds_read_b128 v[130:133], v142
	ds_read_b128 v[134:137], v142 offset:1024
	ds_read_b128 v[138:141], v142 offset:2048
	ds_read_b128 v[142:145], v142 offset:3072
	s_cmp_eq_u32 s69, 12
	s_cselect_b32 s57, s21, s22
	s_cselect_b32 s56, s34, s1
	s_cselect_b32 s31, s47, s68
	s_cselect_b32 s30, s49, s67
	v_lshl_add_u64 v[176:177], s[28:29], 0, v[178:179]
	s_add_i32 m0, s59, 0xc000
	ds_read_b128 v[146:149], v197
	ds_read_b128 v[150:153], v197 offset:1024
	ds_read_b128 v[182:185], v197 offset:2048
	ds_read_b128 v[186:189], v197 offset:3072
	ds_read_b128 v[190:193], v197 offset:4096
	ds_read_b128 v[198:201], v197 offset:5120
	ds_read_b128 v[202:205], v197 offset:6144
	ds_read_b128 v[206:209], v197 offset:7168
	global_load_lds_dwordx4 v[176:177], off
	v_lshl_add_u64 v[176:177], s[28:29], 0, v[180:181]
	s_add_i32 m0, s59, 0xe000
	s_nop 0
	global_load_lds_dwordx4 v[176:177], off
	s_add_i32 s1, 0, 0x14000
	v_add_u32_e32 v168, s1, v195
	ds_read_b128 v[216:219], v168
	ds_read_b128 v[230:233], v168 offset:1024
	ds_read_b128 v[234:237], v168 offset:2048
	ds_read_b128 v[238:241], v168 offset:3072
	s_waitcnt vmcnt(8)
	s_waitcnt lgkmcnt(0)
	s_barrier
	s_setprio 1
	v_mfma_f32_16x16x32_bf16 v[126:129], v[130:133], v[146:149], 0
	v_mfma_f32_16x16x32_bf16 v[122:125], v[138:141], v[146:149], 0
	v_mfma_f32_16x16x32_bf16 v[110:113], v[130:133], v[182:185], 0
	v_mfma_f32_16x16x32_bf16 v[106:109], v[138:141], v[182:185], 0
	v_mfma_f32_16x16x32_bf16 v[94:97], v[130:133], v[190:193], 0
	v_mfma_f32_16x16x32_bf16 v[90:93], v[138:141], v[190:193], 0
	v_mfma_f32_16x16x32_bf16 v[78:81], v[130:133], v[202:205], 0
	v_mfma_f32_16x16x32_bf16 v[74:77], v[138:141], v[202:205], 0
	v_mfma_f32_16x16x32_bf16 v[126:129], v[134:137], v[150:153], v[126:129]
	v_mfma_f32_16x16x32_bf16 v[122:125], v[142:145], v[150:153], v[122:125]
	v_mfma_f32_16x16x32_bf16 v[110:113], v[134:137], v[186:189], v[110:113]
	v_mfma_f32_16x16x32_bf16 v[106:109], v[142:145], v[186:189], v[106:109]
	v_mfma_f32_16x16x32_bf16 v[94:97], v[134:137], v[198:201], v[94:97]
	v_mfma_f32_16x16x32_bf16 v[90:93], v[142:145], v[198:201], v[90:93]
	v_mfma_f32_16x16x32_bf16 v[78:81], v[134:137], v[206:209], v[78:81]
	v_mfma_f32_16x16x32_bf16 v[74:77], v[142:145], v[206:209], v[74:77]
	v_mfma_f32_16x16x32_bf16 v[118:121], v[216:219], v[146:149], 0
	v_mfma_f32_16x16x32_bf16 v[114:117], v[234:237], v[146:149], 0
	v_mfma_f32_16x16x32_bf16 v[102:105], v[216:219], v[182:185], 0
	v_mfma_f32_16x16x32_bf16 v[98:101], v[234:237], v[182:185], 0
	v_mfma_f32_16x16x32_bf16 v[86:89], v[216:219], v[190:193], 0
	v_mfma_f32_16x16x32_bf16 v[82:85], v[234:237], v[190:193], 0
	v_mfma_f32_16x16x32_bf16 v[70:73], v[216:219], v[202:205], 0
	v_mfma_f32_16x16x32_bf16 v[66:69], v[234:237], v[202:205], 0
	v_mfma_f32_16x16x32_bf16 v[118:121], v[230:233], v[150:153], v[118:121]
	v_mfma_f32_16x16x32_bf16 v[114:117], v[238:241], v[150:153], v[114:117]
	v_mfma_f32_16x16x32_bf16 v[102:105], v[230:233], v[186:189], v[102:105]
	v_mfma_f32_16x16x32_bf16 v[98:101], v[238:241], v[186:189], v[98:101]
	v_mfma_f32_16x16x32_bf16 v[86:89], v[230:233], v[198:201], v[86:89]
	v_mfma_f32_16x16x32_bf16 v[82:85], v[238:241], v[198:201], v[82:85]
	v_mfma_f32_16x16x32_bf16 v[70:73], v[230:233], v[206:209], v[70:73]
	v_mfma_f32_16x16x32_bf16 v[66:69], v[238:241], v[206:209], v[66:69]
	s_setprio 0
	s_barrier
	ds_read_b128 v[146:149], v197 offset:16384
	ds_read_b128 v[150:153], v197 offset:17408
	ds_read_b128 v[182:185], v197 offset:18432
	ds_read_b128 v[186:189], v197 offset:19456
	ds_read_b128 v[190:193], v197 offset:20480
	ds_read_b128 v[198:201], v197 offset:21504
	ds_read_b128 v[202:205], v197 offset:22528
	ds_read_b128 v[206:209], v197 offset:23552
	s_add_i32 s22, s23, s58
	v_lshl_add_u64 v[176:177], s[30:31], 0, v[0:1]
	s_mov_b32 m0, s22
	s_nop 0
	global_load_lds_dwordx4 v[176:177], off
	v_lshl_add_u64 v[220:221], s[30:31], 0, v[154:155]
	s_add_i32 m0, s22, 0x2000
	s_nop 0
	global_load_lds_dwordx4 v[220:221], off
	s_mov_b32 m0, s59
	v_lshl_add_u64 v[242:243], s[56:57], 0, v[158:159]
	global_load_lds_dwordx4 v[242:243], off
	v_lshl_add_u64 v[244:245], s[56:57], 0, v[156:157]
	s_mov_b32 m0, s60
	s_nop 0
	global_load_lds_dwordx4 v[244:245], off
	s_add_u32 s22, s30, 0x40000
	s_addc_u32 s23, s31, 0
	s_add_i32 s1, s1, s58
	s_mov_b32 m0, s1
	s_nop 0
	global_load_lds_dwordx4 v0, s[22:23]
	s_add_i32 m0, s1, 0x2000
	s_nop 0
	global_load_lds_dwordx4 v154, s[22:23]
	s_waitcnt vmcnt(8)
	s_waitcnt lgkmcnt(0)
	s_barrier
	s_setprio 1
	v_mfma_f32_16x16x32_bf16 v[62:65], v[130:133], v[146:149], 0
	v_mfma_f32_16x16x32_bf16 v[58:61], v[138:141], v[146:149], 0
	v_mfma_f32_16x16x32_bf16 v[46:49], v[130:133], v[182:185], 0
	v_mfma_f32_16x16x32_bf16 v[42:45], v[138:141], v[182:185], 0
	v_mfma_f32_16x16x32_bf16 v[30:33], v[130:133], v[190:193], 0
	v_mfma_f32_16x16x32_bf16 v[26:29], v[138:141], v[190:193], 0
	v_mfma_f32_16x16x32_bf16 v[14:17], v[130:133], v[202:205], 0
	v_mfma_f32_16x16x32_bf16 v[10:13], v[138:141], v[202:205], 0
	v_mfma_f32_16x16x32_bf16 v[62:65], v[134:137], v[150:153], v[62:65]
	v_mfma_f32_16x16x32_bf16 v[58:61], v[142:145], v[150:153], v[58:61]
	v_mfma_f32_16x16x32_bf16 v[46:49], v[134:137], v[186:189], v[46:49]
	v_mfma_f32_16x16x32_bf16 v[42:45], v[142:145], v[186:189], v[42:45]
	v_mfma_f32_16x16x32_bf16 v[30:33], v[134:137], v[198:201], v[30:33]
	v_mfma_f32_16x16x32_bf16 v[26:29], v[142:145], v[198:201], v[26:29]
	v_mfma_f32_16x16x32_bf16 v[14:17], v[134:137], v[206:209], v[14:17]
	v_mfma_f32_16x16x32_bf16 v[10:13], v[142:145], v[206:209], v[10:13]
	v_mfma_f32_16x16x32_bf16 v[54:57], v[216:219], v[146:149], 0
	v_mfma_f32_16x16x32_bf16 v[50:53], v[234:237], v[146:149], 0
	v_mfma_f32_16x16x32_bf16 v[38:41], v[216:219], v[182:185], 0
	v_mfma_f32_16x16x32_bf16 v[34:37], v[234:237], v[182:185], 0
	v_mfma_f32_16x16x32_bf16 v[22:25], v[216:219], v[190:193], 0
	v_mfma_f32_16x16x32_bf16 v[18:21], v[234:237], v[190:193], 0
	v_mfma_f32_16x16x32_bf16 v[6:9], v[216:219], v[202:205], 0
	v_mfma_f32_16x16x32_bf16 v[2:5], v[234:237], v[202:205], 0
	v_mfma_f32_16x16x32_bf16 v[54:57], v[230:233], v[150:153], v[54:57]
	v_mfma_f32_16x16x32_bf16 v[50:53], v[238:241], v[150:153], v[50:53]
	v_mfma_f32_16x16x32_bf16 v[38:41], v[230:233], v[186:189], v[38:41]
	v_mfma_f32_16x16x32_bf16 v[34:37], v[238:241], v[186:189], v[34:37]
	v_mfma_f32_16x16x32_bf16 v[22:25], v[230:233], v[198:201], v[22:25]
	v_mfma_f32_16x16x32_bf16 v[18:21], v[238:241], v[198:201], v[18:21]
	v_mfma_f32_16x16x32_bf16 v[6:9], v[230:233], v[206:209], v[6:9]
	v_mfma_f32_16x16x32_bf16 v[2:5], v[238:241], v[206:209], v[2:5]
	s_setprio 0
	s_barrier
	s_add_i32 s1, 0, 0x18000
	v_add_u32_e32 v142, s1, v195
	ds_read_b128 v[130:133], v142
	ds_read_b128 v[134:137], v142 offset:1024
	ds_read_b128 v[138:141], v142 offset:2048
	ds_read_b128 v[142:145], v142 offset:3072
	s_add_u32 s22, s56, 0x40000
	s_addc_u32 s23, s57, 0
	s_mov_b32 m0, s61
	v_lshl_add_u64 v[216:217], s[22:23], 0, v[158:159]
	ds_read_b128 v[146:149], v197 offset:32768
	ds_read_b128 v[150:153], v197 offset:33792
	ds_read_b128 v[182:185], v197 offset:34816
	ds_read_b128 v[186:189], v197 offset:35840
	ds_read_b128 v[190:193], v197 offset:36864
	ds_read_b128 v[198:201], v197 offset:37888
	ds_read_b128 v[202:205], v197 offset:38912
	ds_read_b128 v[206:209], v197 offset:39936
	global_load_lds_dwordx4 v[216:217], off
	v_lshl_add_u64 v[216:217], s[22:23], 0, v[156:157]
	s_mov_b32 m0, s62
	s_nop 0
	global_load_lds_dwordx4 v[216:217], off
	s_add_i32 s33, 0, 0x1c000
	v_add_u32_e32 v168, s33, v195
	ds_read_b128 v[216:219], v168
	ds_read_b128 v[230:233], v168 offset:1024
	ds_read_b128 v[234:237], v168 offset:2048
	ds_read_b128 v[238:241], v168 offset:3072
	s_waitcnt vmcnt(8)
	s_waitcnt lgkmcnt(0)
	s_barrier
	s_setprio 1
	v_mfma_f32_16x16x32_bf16 v[126:129], v[130:133], v[146:149], v[126:129]
	v_mfma_f32_16x16x32_bf16 v[122:125], v[138:141], v[146:149], v[122:125]
	v_mfma_f32_16x16x32_bf16 v[110:113], v[130:133], v[182:185], v[110:113]
	v_mfma_f32_16x16x32_bf16 v[106:109], v[138:141], v[182:185], v[106:109]
	v_mfma_f32_16x16x32_bf16 v[94:97], v[130:133], v[190:193], v[94:97]
	v_mfma_f32_16x16x32_bf16 v[90:93], v[138:141], v[190:193], v[90:93]
	v_mfma_f32_16x16x32_bf16 v[78:81], v[130:133], v[202:205], v[78:81]
	v_mfma_f32_16x16x32_bf16 v[74:77], v[138:141], v[202:205], v[74:77]
	v_mfma_f32_16x16x32_bf16 v[126:129], v[134:137], v[150:153], v[126:129]
	v_mfma_f32_16x16x32_bf16 v[122:125], v[142:145], v[150:153], v[122:125]
	v_mfma_f32_16x16x32_bf16 v[110:113], v[134:137], v[186:189], v[110:113]
	v_mfma_f32_16x16x32_bf16 v[106:109], v[142:145], v[186:189], v[106:109]
	v_mfma_f32_16x16x32_bf16 v[94:97], v[134:137], v[198:201], v[94:97]
	v_mfma_f32_16x16x32_bf16 v[90:93], v[142:145], v[198:201], v[90:93]
	v_mfma_f32_16x16x32_bf16 v[78:81], v[134:137], v[206:209], v[78:81]
	v_mfma_f32_16x16x32_bf16 v[74:77], v[142:145], v[206:209], v[74:77]
	v_mfma_f32_16x16x32_bf16 v[118:121], v[216:219], v[146:149], v[118:121]
	v_mfma_f32_16x16x32_bf16 v[114:117], v[234:237], v[146:149], v[114:117]
	v_mfma_f32_16x16x32_bf16 v[102:105], v[216:219], v[182:185], v[102:105]
	v_mfma_f32_16x16x32_bf16 v[98:101], v[234:237], v[182:185], v[98:101]
	v_mfma_f32_16x16x32_bf16 v[86:89], v[216:219], v[190:193], v[86:89]
	v_mfma_f32_16x16x32_bf16 v[82:85], v[234:237], v[190:193], v[82:85]
	v_mfma_f32_16x16x32_bf16 v[70:73], v[216:219], v[202:205], v[70:73]
	v_mfma_f32_16x16x32_bf16 v[66:69], v[234:237], v[202:205], v[66:69]
	v_mfma_f32_16x16x32_bf16 v[118:121], v[230:233], v[150:153], v[118:121]
	v_mfma_f32_16x16x32_bf16 v[114:117], v[238:241], v[150:153], v[114:117]
	v_mfma_f32_16x16x32_bf16 v[102:105], v[230:233], v[186:189], v[102:105]
	v_mfma_f32_16x16x32_bf16 v[98:101], v[238:241], v[186:189], v[98:101]
	v_mfma_f32_16x16x32_bf16 v[86:89], v[230:233], v[198:201], v[86:89]
	v_mfma_f32_16x16x32_bf16 v[82:85], v[238:241], v[198:201], v[82:85]
	v_mfma_f32_16x16x32_bf16 v[70:73], v[230:233], v[206:209], v[70:73]
	v_mfma_f32_16x16x32_bf16 v[66:69], v[238:241], v[206:209], v[66:69]
	s_setprio 0
	s_barrier
	ds_read_b128 v[146:149], v197 offset:49152
	ds_read_b128 v[150:153], v197 offset:50176
	ds_read_b128 v[182:185], v197 offset:51200
	ds_read_b128 v[186:189], v197 offset:52224
	ds_read_b128 v[190:193], v197 offset:53248
	ds_read_b128 v[198:201], v197 offset:54272
	ds_read_b128 v[202:205], v197 offset:55296
	ds_read_b128 v[206:209], v197 offset:56320
	s_add_i32 s1, s1, s58
	v_lshl_add_u64 v[176:177], v[176:177], 0, s[12:13]
	s_mov_b32 m0, s1
	s_nop 0
	global_load_lds_dwordx4 v[176:177], off
	v_lshl_add_u64 v[176:177], v[220:221], 0, s[12:13]
	s_add_i32 m0, s1, 0x2000
	s_nop 0
	global_load_lds_dwordx4 v[176:177], off
	s_mov_b32 m0, s64
	v_lshl_add_u64 v[176:177], v[242:243], 0, s[12:13]
	global_load_lds_dwordx4 v[176:177], off
	v_lshl_add_u64 v[176:177], v[244:245], 0, s[12:13]
	s_mov_b32 m0, s65
	s_nop 0
	global_load_lds_dwordx4 v[176:177], off
	s_add_u32 s22, s30, 0x40080
	s_addc_u32 s23, s31, 0
	s_add_i32 s1, s33, s58
	s_mov_b32 m0, s1
	s_nop 0
	global_load_lds_dwordx4 v0, s[22:23]
	s_add_i32 m0, s1, 0x2000
	s_nop 0
	global_load_lds_dwordx4 v154, s[22:23]
	s_waitcnt vmcnt(8)
	s_waitcnt lgkmcnt(0)
	s_barrier
	s_setprio 1
	v_mfma_f32_16x16x32_bf16 v[62:65], v[130:133], v[146:149], v[62:65]
	v_mfma_f32_16x16x32_bf16 v[58:61], v[138:141], v[146:149], v[58:61]
	v_mfma_f32_16x16x32_bf16 v[46:49], v[130:133], v[182:185], v[46:49]
	v_mfma_f32_16x16x32_bf16 v[42:45], v[138:141], v[182:185], v[42:45]
	v_mfma_f32_16x16x32_bf16 v[30:33], v[130:133], v[190:193], v[30:33]
	v_mfma_f32_16x16x32_bf16 v[26:29], v[138:141], v[190:193], v[26:29]
	v_mfma_f32_16x16x32_bf16 v[14:17], v[130:133], v[202:205], v[14:17]
	v_mfma_f32_16x16x32_bf16 v[10:13], v[138:141], v[202:205], v[10:13]
	v_mfma_f32_16x16x32_bf16 v[62:65], v[134:137], v[150:153], v[62:65]
	v_mfma_f32_16x16x32_bf16 v[58:61], v[142:145], v[150:153], v[58:61]
	v_mfma_f32_16x16x32_bf16 v[46:49], v[134:137], v[186:189], v[46:49]
	v_mfma_f32_16x16x32_bf16 v[42:45], v[142:145], v[186:189], v[42:45]
	v_mfma_f32_16x16x32_bf16 v[30:33], v[134:137], v[198:201], v[30:33]
	v_mfma_f32_16x16x32_bf16 v[26:29], v[142:145], v[198:201], v[26:29]
	v_mfma_f32_16x16x32_bf16 v[14:17], v[134:137], v[206:209], v[14:17]
	v_mfma_f32_16x16x32_bf16 v[10:13], v[142:145], v[206:209], v[10:13]
	v_mfma_f32_16x16x32_bf16 v[54:57], v[216:219], v[146:149], v[54:57]
	v_mfma_f32_16x16x32_bf16 v[50:53], v[234:237], v[146:149], v[50:53]
	v_mfma_f32_16x16x32_bf16 v[38:41], v[216:219], v[182:185], v[38:41]
	v_mfma_f32_16x16x32_bf16 v[34:37], v[234:237], v[182:185], v[34:37]
	v_mfma_f32_16x16x32_bf16 v[22:25], v[216:219], v[190:193], v[22:25]
	v_mfma_f32_16x16x32_bf16 v[18:21], v[234:237], v[190:193], v[18:21]
	v_mfma_f32_16x16x32_bf16 v[6:9], v[216:219], v[202:205], v[6:9]
	v_mfma_f32_16x16x32_bf16 v[2:5], v[234:237], v[202:205], v[2:5]
	v_mfma_f32_16x16x32_bf16 v[54:57], v[230:233], v[150:153], v[54:57]
	v_mfma_f32_16x16x32_bf16 v[50:53], v[238:241], v[150:153], v[50:53]
	v_mfma_f32_16x16x32_bf16 v[38:41], v[230:233], v[186:189], v[38:41]
	v_mfma_f32_16x16x32_bf16 v[34:37], v[238:241], v[186:189], v[34:37]
	v_mfma_f32_16x16x32_bf16 v[22:25], v[230:233], v[198:201], v[22:25]
	v_mfma_f32_16x16x32_bf16 v[18:21], v[238:241], v[198:201], v[18:21]
	v_mfma_f32_16x16x32_bf16 v[6:9], v[230:233], v[206:209], v[6:9]
	v_mfma_f32_16x16x32_bf16 v[2:5], v[238:241], v[206:209], v[2:5]
	s_setprio 0
	s_add_i32 s69, s69, 2
	s_add_u32 s28, s28, 0x100
	s_addc_u32 s29, s29, 0
	s_add_u32 s67, s67, 0x100
	s_addc_u32 s68, s68, 0
	s_cmp_gt_u32 s69, 13
	s_barrier

.LBB0_82:
	s_ashr_i32 s27, s26, 31
	v_mov_b64_e32 v[2:3], 0xb00
	s_lshl_b64 s[22:23], s[26:27], 19
	v_cmp_lt_i64_e32 vcc, s[36:37], v[2:3]
	s_add_u32 s36, s96, s22
	s_addc_u32 s37, s97, s23
	s_and_b64 s[22:23], vcc, exec
	s_cselect_b32 s27, s37, s29
	s_cselect_b32 s56, s36, s28
	s_ashr_i32 s7, s6, 31
	s_lshl_b64 s[22:23], s[6:7], 19
	s_add_u32 s44, s4, s22
	s_addc_u32 s45, s16, s23
	s_and_b64 s[22:23], vcc, exec
	s_cselect_b32 s7, s45, s31
	s_cselect_b32 s57, s44, s30
	s_add_u32 s28, s28, 0x40080
	s_addc_u32 s29, s29, 0
	s_add_u32 s58, s30, 0x100
	s_addc_u32 s59, s31, 0
	s_mov_b32 s60, -2
	s_cmpk_gt_u32 s0, 0xff
	s_cbranch_scc0 .Lrs_i2_pre
	s_barrier
.Lrs_i2_pre:
	s_add_u32 s1, s28, 0xfffc0080
	s_addc_u32 s22, s29, -1
	s_add_i32 s23, 0, 0x10000
	v_add_u32_e32 v142, s23, v201
	ds_read_b128 v[130:133], v142
	ds_read_b128 v[134:137], v142 offset:1024
	ds_read_b128 v[138:141], v142 offset:2048
	ds_read_b128 v[142:145], v142 offset:3072
	s_cmp_eq_u32 s60, 12
	s_cselect_b32 s43, s27, s22
	s_cselect_b32 s42, s56, s1
	s_cselect_b32 s31, s7, s59
	s_cselect_b32 s30, s57, s58
	v_lshl_add_u64 v[176:177], s[28:29], 0, v[178:179]
	s_add_i32 m0, s46, 0xc000
	ds_read_b128 v[146:149], v205
	ds_read_b128 v[150:153], v205 offset:1024
	ds_read_b128 v[182:185], v205 offset:2048
	ds_read_b128 v[186:189], v205 offset:3072
	ds_read_b128 v[190:193], v205 offset:4096
	ds_read_b128 v[194:197], v205 offset:5120
	ds_read_b128 v[206:209], v205 offset:6144
	ds_read_b128 v[216:219], v205 offset:7168
	global_load_lds_dwordx4 v[176:177], off
	v_lshl_add_u64 v[176:177], s[28:29], 0, v[180:181]
	s_add_i32 m0, s46, 0xe000
	s_nop 0
	global_load_lds_dwordx4 v[176:177], off
	s_add_i32 s1, 0, 0x14000
	v_add_u32_e32 v168, s1, v201
	ds_read_b128 v[230:233], v168
	ds_read_b128 v[234:237], v168 offset:1024
	ds_read_b128 v[238:241], v168 offset:2048
	ds_read_b128 v[242:245], v168 offset:3072
	s_waitcnt vmcnt(8)
	s_waitcnt lgkmcnt(0)
	s_barrier
	s_setprio 1
	v_mfma_f32_16x16x32_bf16 v[126:129], v[130:133], v[146:149], 0
	v_mfma_f32_16x16x32_bf16 v[118:121], v[138:141], v[146:149], 0
	v_mfma_f32_16x16x32_bf16 v[110:113], v[130:133], v[182:185], 0
	v_mfma_f32_16x16x32_bf16 v[102:105], v[138:141], v[182:185], 0
	v_mfma_f32_16x16x32_bf16 v[94:97], v[130:133], v[190:193], 0
	v_mfma_f32_16x16x32_bf16 v[86:89], v[138:141], v[190:193], 0
	v_mfma_f32_16x16x32_bf16 v[78:81], v[130:133], v[206:209], 0
	v_mfma_f32_16x16x32_bf16 v[70:73], v[138:141], v[206:209], 0
	v_mfma_f32_16x16x32_bf16 v[126:129], v[134:137], v[150:153], v[126:129]
	v_mfma_f32_16x16x32_bf16 v[118:121], v[142:145], v[150:153], v[118:121]
	v_mfma_f32_16x16x32_bf16 v[110:113], v[134:137], v[186:189], v[110:113]
	v_mfma_f32_16x16x32_bf16 v[102:105], v[142:145], v[186:189], v[102:105]
	v_mfma_f32_16x16x32_bf16 v[94:97], v[134:137], v[194:197], v[94:97]
	v_mfma_f32_16x16x32_bf16 v[86:89], v[142:145], v[194:197], v[86:89]
	v_mfma_f32_16x16x32_bf16 v[78:81], v[134:137], v[216:219], v[78:81]
	v_mfma_f32_16x16x32_bf16 v[70:73], v[142:145], v[216:219], v[70:73]
	v_mfma_f32_16x16x32_bf16 v[122:125], v[230:233], v[146:149], 0
	v_mfma_f32_16x16x32_bf16 v[114:117], v[238:241], v[146:149], 0
	v_mfma_f32_16x16x32_bf16 v[106:109], v[230:233], v[182:185], 0
	v_mfma_f32_16x16x32_bf16 v[98:101], v[238:241], v[182:185], 0
	v_mfma_f32_16x16x32_bf16 v[90:93], v[230:233], v[190:193], 0
	v_mfma_f32_16x16x32_bf16 v[82:85], v[238:241], v[190:193], 0
	v_mfma_f32_16x16x32_bf16 v[74:77], v[230:233], v[206:209], 0
	v_mfma_f32_16x16x32_bf16 v[66:69], v[238:241], v[206:209], 0
	v_mfma_f32_16x16x32_bf16 v[122:125], v[234:237], v[150:153], v[122:125]
	v_mfma_f32_16x16x32_bf16 v[114:117], v[242:245], v[150:153], v[114:117]
	v_mfma_f32_16x16x32_bf16 v[106:109], v[234:237], v[186:189], v[106:109]
	v_mfma_f32_16x16x32_bf16 v[98:101], v[242:245], v[186:189], v[98:101]
	v_mfma_f32_16x16x32_bf16 v[90:93], v[234:237], v[194:197], v[90:93]
	v_mfma_f32_16x16x32_bf16 v[82:85], v[242:245], v[194:197], v[82:85]
	v_mfma_f32_16x16x32_bf16 v[74:77], v[234:237], v[216:219], v[74:77]
	v_mfma_f32_16x16x32_bf16 v[66:69], v[242:245], v[216:219], v[66:69]
	s_setprio 0
	s_barrier
	ds_read_b128 v[146:149], v205 offset:16384
	ds_read_b128 v[150:153], v205 offset:17408
	ds_read_b128 v[182:185], v205 offset:18432
	ds_read_b128 v[186:189], v205 offset:19456
	ds_read_b128 v[190:193], v205 offset:20480
	ds_read_b128 v[194:197], v205 offset:21504
	ds_read_b128 v[206:209], v205 offset:22528
	ds_read_b128 v[216:219], v205 offset:23552
	s_add_i32 s22, s23, s17
	v_lshl_add_u64 v[176:177], s[30:31], 0, v[0:1]
	s_mov_b32 m0, s22
	s_nop 0
	global_load_lds_dwordx4 v[176:177], off
	v_lshl_add_u64 v[202:203], s[30:31], 0, v[154:155]
	s_add_i32 m0, s22, 0x2000
	s_nop 0
	global_load_lds_dwordx4 v[202:203], off
	s_mov_b32 m0, s46
	v_lshl_add_u64 v[220:221], s[42:43], 0, v[158:159]
	global_load_lds_dwordx4 v[220:221], off
	v_lshl_add_u64 v[246:247], s[42:43], 0, v[156:157]
	s_mov_b32 m0, s47
	s_nop 0
	global_load_lds_dwordx4 v[246:247], off
	s_add_u32 s22, s30, 0x40000
	s_addc_u32 s23, s31, 0
	s_add_i32 s1, s1, s17
	s_mov_b32 m0, s1
	s_nop 0
	global_load_lds_dwordx4 v0, s[22:23]
	s_add_i32 m0, s1, 0x2000
	s_nop 0
	global_load_lds_dwordx4 v154, s[22:23]
	s_waitcnt vmcnt(8)
	s_waitcnt lgkmcnt(0)
	s_barrier
	s_setprio 1
	v_mfma_f32_16x16x32_bf16 v[62:65], v[130:133], v[146:149], 0
	v_mfma_f32_16x16x32_bf16 v[54:57], v[138:141], v[146:149], 0
	v_mfma_f32_16x16x32_bf16 v[46:49], v[130:133], v[182:185], 0
	v_mfma_f32_16x16x32_bf16 v[38:41], v[138:141], v[182:185], 0
	v_mfma_f32_16x16x32_bf16 v[30:33], v[130:133], v[190:193], 0
	v_mfma_f32_16x16x32_bf16 v[22:25], v[138:141], v[190:193], 0
	v_mfma_f32_16x16x32_bf16 v[14:17], v[130:133], v[206:209], 0
	v_mfma_f32_16x16x32_bf16 v[6:9], v[138:141], v[206:209], 0
	v_mfma_f32_16x16x32_bf16 v[62:65], v[134:137], v[150:153], v[62:65]
	v_mfma_f32_16x16x32_bf16 v[54:57], v[142:145], v[150:153], v[54:57]
	v_mfma_f32_16x16x32_bf16 v[46:49], v[134:137], v[186:189], v[46:49]
	v_mfma_f32_16x16x32_bf16 v[38:41], v[142:145], v[186:189], v[38:41]
	v_mfma_f32_16x16x32_bf16 v[30:33], v[134:137], v[194:197], v[30:33]
	v_mfma_f32_16x16x32_bf16 v[22:25], v[142:145], v[194:197], v[22:25]
	v_mfma_f32_16x16x32_bf16 v[14:17], v[134:137], v[216:219], v[14:17]
	v_mfma_f32_16x16x32_bf16 v[6:9], v[142:145], v[216:219], v[6:9]
	v_mfma_f32_16x16x32_bf16 v[58:61], v[230:233], v[146:149], 0
	v_mfma_f32_16x16x32_bf16 v[50:53], v[238:241], v[146:149], 0
	v_mfma_f32_16x16x32_bf16 v[42:45], v[230:233], v[182:185], 0
	v_mfma_f32_16x16x32_bf16 v[34:37], v[238:241], v[182:185], 0
	v_mfma_f32_16x16x32_bf16 v[26:29], v[230:233], v[190:193], 0
	v_mfma_f32_16x16x32_bf16 v[18:21], v[238:241], v[190:193], 0
	v_mfma_f32_16x16x32_bf16 v[10:13], v[230:233], v[206:209], 0
	v_mfma_f32_16x16x32_bf16 v[2:5], v[238:241], v[206:209], 0
	v_mfma_f32_16x16x32_bf16 v[58:61], v[234:237], v[150:153], v[58:61]
	v_mfma_f32_16x16x32_bf16 v[50:53], v[242:245], v[150:153], v[50:53]
	v_mfma_f32_16x16x32_bf16 v[42:45], v[234:237], v[186:189], v[42:45]
	v_mfma_f32_16x16x32_bf16 v[34:37], v[242:245], v[186:189], v[34:37]
	v_mfma_f32_16x16x32_bf16 v[26:29], v[234:237], v[194:197], v[26:29]
	v_mfma_f32_16x16x32_bf16 v[18:21], v[242:245], v[194:197], v[18:21]
	v_mfma_f32_16x16x32_bf16 v[10:13], v[234:237], v[216:219], v[10:13]
	v_mfma_f32_16x16x32_bf16 v[2:5], v[242:245], v[216:219], v[2:5]
	s_setprio 0
	s_barrier
	s_add_i32 s1, 0, 0x18000
	v_add_u32_e32 v142, s1, v201
	ds_read_b128 v[130:133], v142
	ds_read_b128 v[134:137], v142 offset:1024
	ds_read_b128 v[138:141], v142 offset:2048
	ds_read_b128 v[142:145], v142 offset:3072
	s_add_u32 s22, s42, 0x40000
	s_addc_u32 s23, s43, 0
	s_mov_b32 m0, s48
	v_lshl_add_u64 v[230:231], s[22:23], 0, v[158:159]
	ds_read_b128 v[146:149], v205 offset:32768
	ds_read_b128 v[150:153], v205 offset:33792
	ds_read_b128 v[182:185], v205 offset:34816
	ds_read_b128 v[186:189], v205 offset:35840
	ds_read_b128 v[190:193], v205 offset:36864
	ds_read_b128 v[194:197], v205 offset:37888
	ds_read_b128 v[206:209], v205 offset:38912
	ds_read_b128 v[216:219], v205 offset:39936
	global_load_lds_dwordx4 v[230:231], off
	v_lshl_add_u64 v[230:231], s[22:23], 0, v[156:157]
	s_mov_b32 m0, s49
	s_nop 0
	global_load_lds_dwordx4 v[230:231], off
	s_add_i32 s33, 0, 0x1c000
	v_add_u32_e32 v168, s33, v201
	ds_read_b128 v[230:233], v168
	ds_read_b128 v[234:237], v168 offset:1024
	ds_read_b128 v[238:241], v168 offset:2048
	ds_read_b128 v[242:245], v168 offset:3072
	s_waitcnt vmcnt(8)
	s_waitcnt lgkmcnt(0)
	s_barrier
	s_setprio 1
	v_mfma_f32_16x16x32_bf16 v[126:129], v[130:133], v[146:149], v[126:129]
	v_mfma_f32_16x16x32_bf16 v[118:121], v[138:141], v[146:149], v[118:121]
	v_mfma_f32_16x16x32_bf16 v[110:113], v[130:133], v[182:185], v[110:113]
	v_mfma_f32_16x16x32_bf16 v[102:105], v[138:141], v[182:185], v[102:105]
	v_mfma_f32_16x16x32_bf16 v[94:97], v[130:133], v[190:193], v[94:97]
	v_mfma_f32_16x16x32_bf16 v[86:89], v[138:141], v[190:193], v[86:89]
	v_mfma_f32_16x16x32_bf16 v[78:81], v[130:133], v[206:209], v[78:81]
	v_mfma_f32_16x16x32_bf16 v[70:73], v[138:141], v[206:209], v[70:73]
	v_mfma_f32_16x16x32_bf16 v[126:129], v[134:137], v[150:153], v[126:129]
	v_mfma_f32_16x16x32_bf16 v[118:121], v[142:145], v[150:153], v[118:121]
	v_mfma_f32_16x16x32_bf16 v[110:113], v[134:137], v[186:189], v[110:113]
	v_mfma_f32_16x16x32_bf16 v[102:105], v[142:145], v[186:189], v[102:105]
	v_mfma_f32_16x16x32_bf16 v[94:97], v[134:137], v[194:197], v[94:97]
	v_mfma_f32_16x16x32_bf16 v[86:89], v[142:145], v[194:197], v[86:89]
	v_mfma_f32_16x16x32_bf16 v[78:81], v[134:137], v[216:219], v[78:81]
	v_mfma_f32_16x16x32_bf16 v[70:73], v[142:145], v[216:219], v[70:73]
	v_mfma_f32_16x16x32_bf16 v[122:125], v[230:233], v[146:149], v[122:125]
	v_mfma_f32_16x16x32_bf16 v[114:117], v[238:241], v[146:149], v[114:117]
	v_mfma_f32_16x16x32_bf16 v[106:109], v[230:233], v[182:185], v[106:109]
	v_mfma_f32_16x16x32_bf16 v[98:101], v[238:241], v[182:185], v[98:101]
	v_mfma_f32_16x16x32_bf16 v[90:93], v[230:233], v[190:193], v[90:93]
	v_mfma_f32_16x16x32_bf16 v[82:85], v[238:241], v[190:193], v[82:85]
	v_mfma_f32_16x16x32_bf16 v[74:77], v[230:233], v[206:209], v[74:77]
	v_mfma_f32_16x16x32_bf16 v[66:69], v[238:241], v[206:209], v[66:69]
	v_mfma_f32_16x16x32_bf16 v[122:125], v[234:237], v[150:153], v[122:125]
	v_mfma_f32_16x16x32_bf16 v[114:117], v[242:245], v[150:153], v[114:117]
	v_mfma_f32_16x16x32_bf16 v[106:109], v[234:237], v[186:189], v[106:109]
	v_mfma_f32_16x16x32_bf16 v[98:101], v[242:245], v[186:189], v[98:101]
	v_mfma_f32_16x16x32_bf16 v[90:93], v[234:237], v[194:197], v[90:93]
	v_mfma_f32_16x16x32_bf16 v[82:85], v[242:245], v[194:197], v[82:85]
	v_mfma_f32_16x16x32_bf16 v[74:77], v[234:237], v[216:219], v[74:77]
	v_mfma_f32_16x16x32_bf16 v[66:69], v[242:245], v[216:219], v[66:69]
	s_setprio 0
	s_barrier
	ds_read_b128 v[146:149], v205 offset:49152
	ds_read_b128 v[150:153], v205 offset:50176
	ds_read_b128 v[182:185], v205 offset:51200
	ds_read_b128 v[186:189], v205 offset:52224
	ds_read_b128 v[190:193], v205 offset:53248
	ds_read_b128 v[194:197], v205 offset:54272
	ds_read_b128 v[206:209], v205 offset:55296
	ds_read_b128 v[216:219], v205 offset:56320
	s_add_i32 s1, s1, s17
	v_lshl_add_u64 v[176:177], v[176:177], 0, s[12:13]
	s_mov_b32 m0, s1
	s_nop 0
	global_load_lds_dwordx4 v[176:177], off
	v_lshl_add_u64 v[176:177], v[202:203], 0, s[12:13]
	s_add_i32 m0, s1, 0x2000
	s_nop 0
	global_load_lds_dwordx4 v[176:177], off
	s_mov_b32 m0, s20
	v_lshl_add_u64 v[176:177], v[220:221], 0, s[12:13]
	global_load_lds_dwordx4 v[176:177], off
	v_lshl_add_u64 v[176:177], v[246:247], 0, s[12:13]
	s_mov_b32 m0, s21
	s_nop 0
	global_load_lds_dwordx4 v[176:177], off
	s_add_u32 s22, s30, 0x40080
	s_addc_u32 s23, s31, 0
	s_add_i32 s1, s33, s17
	s_mov_b32 m0, s1
	s_nop 0
	global_load_lds_dwordx4 v0, s[22:23]
	s_add_i32 m0, s1, 0x2000
	s_nop 0
	global_load_lds_dwordx4 v154, s[22:23]
	s_waitcnt vmcnt(8)
	s_waitcnt lgkmcnt(0)
	s_barrier
	s_setprio 1
	v_mfma_f32_16x16x32_bf16 v[62:65], v[130:133], v[146:149], v[62:65]
	v_mfma_f32_16x16x32_bf16 v[54:57], v[138:141], v[146:149], v[54:57]
	v_mfma_f32_16x16x32_bf16 v[46:49], v[130:133], v[182:185], v[46:49]
	v_mfma_f32_16x16x32_bf16 v[38:41], v[138:141], v[182:185], v[38:41]
	v_mfma_f32_16x16x32_bf16 v[30:33], v[130:133], v[190:193], v[30:33]
	v_mfma_f32_16x16x32_bf16 v[22:25], v[138:141], v[190:193], v[22:25]
	v_mfma_f32_16x16x32_bf16 v[14:17], v[130:133], v[206:209], v[14:17]
	v_mfma_f32_16x16x32_bf16 v[6:9], v[138:141], v[206:209], v[6:9]
	v_mfma_f32_16x16x32_bf16 v[62:65], v[134:137], v[150:153], v[62:65]
	v_mfma_f32_16x16x32_bf16 v[54:57], v[142:145], v[150:153], v[54:57]
	v_mfma_f32_16x16x32_bf16 v[46:49], v[134:137], v[186:189], v[46:49]
	v_mfma_f32_16x16x32_bf16 v[38:41], v[142:145], v[186:189], v[38:41]
	v_mfma_f32_16x16x32_bf16 v[30:33], v[134:137], v[194:197], v[30:33]
	v_mfma_f32_16x16x32_bf16 v[22:25], v[142:145], v[194:197], v[22:25]
	v_mfma_f32_16x16x32_bf16 v[14:17], v[134:137], v[216:219], v[14:17]
	v_mfma_f32_16x16x32_bf16 v[6:9], v[142:145], v[216:219], v[6:9]
	v_mfma_f32_16x16x32_bf16 v[58:61], v[230:233], v[146:149], v[58:61]
	v_mfma_f32_16x16x32_bf16 v[50:53], v[238:241], v[146:149], v[50:53]
	v_mfma_f32_16x16x32_bf16 v[42:45], v[230:233], v[182:185], v[42:45]
	v_mfma_f32_16x16x32_bf16 v[34:37], v[238:241], v[182:185], v[34:37]
	v_mfma_f32_16x16x32_bf16 v[26:29], v[230:233], v[190:193], v[26:29]
	v_mfma_f32_16x16x32_bf16 v[18:21], v[238:241], v[190:193], v[18:21]
	v_mfma_f32_16x16x32_bf16 v[10:13], v[230:233], v[206:209], v[10:13]
	v_mfma_f32_16x16x32_bf16 v[2:5], v[238:241], v[206:209], v[2:5]
	v_mfma_f32_16x16x32_bf16 v[58:61], v[234:237], v[150:153], v[58:61]
	v_mfma_f32_16x16x32_bf16 v[50:53], v[242:245], v[150:153], v[50:53]
	v_mfma_f32_16x16x32_bf16 v[42:45], v[234:237], v[186:189], v[42:45]
	v_mfma_f32_16x16x32_bf16 v[34:37], v[242:245], v[186:189], v[34:37]
	v_mfma_f32_16x16x32_bf16 v[26:29], v[234:237], v[194:197], v[26:29]
	v_mfma_f32_16x16x32_bf16 v[18:21], v[242:245], v[194:197], v[18:21]
	v_mfma_f32_16x16x32_bf16 v[10:13], v[234:237], v[216:219], v[10:13]
	v_mfma_f32_16x16x32_bf16 v[2:5], v[242:245], v[216:219], v[2:5]
	s_setprio 0
	s_add_i32 s60, s60, 2
	s_add_u32 s28, s28, 0x100
	s_addc_u32 s29, s29, 0
	s_add_u32 s58, s58, 0x100
	s_addc_u32 s59, s59, 0
	s_cmp_gt_u32 s60, 13
	s_barrier
.LBB0_83:
	s_add_u32 s1, s28, 0xfffc0080
	s_addc_u32 s22, s29, -1
	s_add_i32 s23, 0, 0x10000
	v_add_u32_e32 v142, s23, v201
	ds_read_b128 v[130:133], v142
	ds_read_b128 v[134:137], v142 offset:1024
	ds_read_b128 v[138:141], v142 offset:2048
	ds_read_b128 v[142:145], v142 offset:3072
	s_cmp_eq_u32 s60, 12
	s_cselect_b32 s43, s27, s22
	s_cselect_b32 s42, s56, s1
	s_cselect_b32 s31, s7, s59
	s_cselect_b32 s30, s57, s58
	v_lshl_add_u64 v[176:177], s[28:29], 0, v[178:179]
	s_add_i32 m0, s46, 0xc000
	ds_read_b128 v[146:149], v205
	ds_read_b128 v[150:153], v205 offset:1024
	ds_read_b128 v[182:185], v205 offset:2048
	ds_read_b128 v[186:189], v205 offset:3072
	ds_read_b128 v[190:193], v205 offset:4096
	ds_read_b128 v[194:197], v205 offset:5120
	ds_read_b128 v[206:209], v205 offset:6144
	ds_read_b128 v[216:219], v205 offset:7168
	global_load_lds_dwordx4 v[176:177], off
	v_lshl_add_u64 v[176:177], s[28:29], 0, v[180:181]
	s_add_i32 m0, s46, 0xe000
	s_nop 0
	global_load_lds_dwordx4 v[176:177], off
	s_add_i32 s1, 0, 0x14000
	v_add_u32_e32 v168, s1, v201
	ds_read_b128 v[230:233], v168
	ds_read_b128 v[234:237], v168 offset:1024
	ds_read_b128 v[238:241], v168 offset:2048
	ds_read_b128 v[242:245], v168 offset:3072
	s_waitcnt vmcnt(8)
	s_waitcnt lgkmcnt(0)
	s_barrier
	s_setprio 1
	v_mfma_f32_16x16x32_bf16 v[126:129], v[130:133], v[146:149], v[126:129]
	v_mfma_f32_16x16x32_bf16 v[118:121], v[138:141], v[146:149], v[118:121]
	v_mfma_f32_16x16x32_bf16 v[110:113], v[130:133], v[182:185], v[110:113]
	v_mfma_f32_16x16x32_bf16 v[102:105], v[138:141], v[182:185], v[102:105]
	v_mfma_f32_16x16x32_bf16 v[94:97], v[130:133], v[190:193], v[94:97]
	v_mfma_f32_16x16x32_bf16 v[86:89], v[138:141], v[190:193], v[86:89]
	v_mfma_f32_16x16x32_bf16 v[78:81], v[130:133], v[206:209], v[78:81]
	v_mfma_f32_16x16x32_bf16 v[70:73], v[138:141], v[206:209], v[70:73]
	v_mfma_f32_16x16x32_bf16 v[126:129], v[134:137], v[150:153], v[126:129]
	v_mfma_f32_16x16x32_bf16 v[118:121], v[142:145], v[150:153], v[118:121]
	v_mfma_f32_16x16x32_bf16 v[110:113], v[134:137], v[186:189], v[110:113]
	v_mfma_f32_16x16x32_bf16 v[102:105], v[142:145], v[186:189], v[102:105]
	v_mfma_f32_16x16x32_bf16 v[94:97], v[134:137], v[194:197], v[94:97]
	v_mfma_f32_16x16x32_bf16 v[86:89], v[142:145], v[194:197], v[86:89]
	v_mfma_f32_16x16x32_bf16 v[78:81], v[134:137], v[216:219], v[78:81]
	v_mfma_f32_16x16x32_bf16 v[70:73], v[142:145], v[216:219], v[70:73]
	v_mfma_f32_16x16x32_bf16 v[122:125], v[230:233], v[146:149], v[122:125]
	v_mfma_f32_16x16x32_bf16 v[114:117], v[238:241], v[146:149], v[114:117]
	v_mfma_f32_16x16x32_bf16 v[106:109], v[230:233], v[182:185], v[106:109]
	v_mfma_f32_16x16x32_bf16 v[98:101], v[238:241], v[182:185], v[98:101]
	v_mfma_f32_16x16x32_bf16 v[90:93], v[230:233], v[190:193], v[90:93]
	v_mfma_f32_16x16x32_bf16 v[82:85], v[238:241], v[190:193], v[82:85]
	v_mfma_f32_16x16x32_bf16 v[74:77], v[230:233], v[206:209], v[74:77]
	v_mfma_f32_16x16x32_bf16 v[66:69], v[238:241], v[206:209], v[66:69]
	v_mfma_f32_16x16x32_bf16 v[122:125], v[234:237], v[150:153], v[122:125]
	v_mfma_f32_16x16x32_bf16 v[114:117], v[242:245], v[150:153], v[114:117]
	v_mfma_f32_16x16x32_bf16 v[106:109], v[234:237], v[186:189], v[106:109]
	v_mfma_f32_16x16x32_bf16 v[98:101], v[242:245], v[186:189], v[98:101]
	v_mfma_f32_16x16x32_bf16 v[90:93], v[234:237], v[194:197], v[90:93]
	v_mfma_f32_16x16x32_bf16 v[82:85], v[242:245], v[194:197], v[82:85]
	v_mfma_f32_16x16x32_bf16 v[74:77], v[234:237], v[216:219], v[74:77]
	v_mfma_f32_16x16x32_bf16 v[66:69], v[242:245], v[216:219], v[66:69]
	s_setprio 0
	s_barrier
	ds_read_b128 v[146:149], v205 offset:16384
	ds_read_b128 v[150:153], v205 offset:17408
	ds_read_b128 v[182:185], v205 offset:18432
	ds_read_b128 v[186:189], v205 offset:19456
	ds_read_b128 v[190:193], v205 offset:20480
	ds_read_b128 v[194:197], v205 offset:21504
	ds_read_b128 v[206:209], v205 offset:22528
	ds_read_b128 v[216:219], v205 offset:23552
	s_add_i32 s22, s23, s17
	v_lshl_add_u64 v[176:177], s[30:31], 0, v[0:1]
	s_mov_b32 m0, s22
	s_nop 0
	global_load_lds_dwordx4 v[176:177], off
	v_lshl_add_u64 v[202:203], s[30:31], 0, v[154:155]
	s_add_i32 m0, s22, 0x2000
	s_nop 0
	global_load_lds_dwordx4 v[202:203], off
	s_mov_b32 m0, s46
	v_lshl_add_u64 v[220:221], s[42:43], 0, v[158:159]
	global_load_lds_dwordx4 v[220:221], off
	v_lshl_add_u64 v[246:247], s[42:43], 0, v[156:157]
	s_mov_b32 m0, s47
	s_nop 0
	global_load_lds_dwordx4 v[246:247], off
	s_add_u32 s22, s30, 0x40000
	s_addc_u32 s23, s31, 0
	s_add_i32 s1, s1, s17
	s_mov_b32 m0, s1
	s_nop 0
	global_load_lds_dwordx4 v0, s[22:23]
	s_add_i32 m0, s1, 0x2000
	s_nop 0
	global_load_lds_dwordx4 v154, s[22:23]
	s_waitcnt vmcnt(8)
	s_waitcnt lgkmcnt(0)
	s_barrier
	s_setprio 1
	v_mfma_f32_16x16x32_bf16 v[62:65], v[130:133], v[146:149], v[62:65]
	v_mfma_f32_16x16x32_bf16 v[54:57], v[138:141], v[146:149], v[54:57]
	v_mfma_f32_16x16x32_bf16 v[46:49], v[130:133], v[182:185], v[46:49]
	v_mfma_f32_16x16x32_bf16 v[38:41], v[138:141], v[182:185], v[38:41]
	v_mfma_f32_16x16x32_bf16 v[30:33], v[130:133], v[190:193], v[30:33]
	v_mfma_f32_16x16x32_bf16 v[22:25], v[138:141], v[190:193], v[22:25]
	v_mfma_f32_16x16x32_bf16 v[14:17], v[130:133], v[206:209], v[14:17]
	v_mfma_f32_16x16x32_bf16 v[6:9], v[138:141], v[206:209], v[6:9]
	v_mfma_f32_16x16x32_bf16 v[62:65], v[134:137], v[150:153], v[62:65]
	v_mfma_f32_16x16x32_bf16 v[54:57], v[142:145], v[150:153], v[54:57]
	v_mfma_f32_16x16x32_bf16 v[46:49], v[134:137], v[186:189], v[46:49]
	v_mfma_f32_16x16x32_bf16 v[38:41], v[142:145], v[186:189], v[38:41]
	v_mfma_f32_16x16x32_bf16 v[30:33], v[134:137], v[194:197], v[30:33]
	v_mfma_f32_16x16x32_bf16 v[22:25], v[142:145], v[194:197], v[22:25]
	v_mfma_f32_16x16x32_bf16 v[14:17], v[134:137], v[216:219], v[14:17]
	v_mfma_f32_16x16x32_bf16 v[6:9], v[142:145], v[216:219], v[6:9]
	v_mfma_f32_16x16x32_bf16 v[58:61], v[230:233], v[146:149], v[58:61]
	v_mfma_f32_16x16x32_bf16 v[50:53], v[238:241], v[146:149], v[50:53]
	v_mfma_f32_16x16x32_bf16 v[42:45], v[230:233], v[182:185], v[42:45]
	v_mfma_f32_16x16x32_bf16 v[34:37], v[238:241], v[182:185], v[34:37]
	v_mfma_f32_16x16x32_bf16 v[26:29], v[230:233], v[190:193], v[26:29]
	v_mfma_f32_16x16x32_bf16 v[18:21], v[238:241], v[190:193], v[18:21]
	v_mfma_f32_16x16x32_bf16 v[10:13], v[230:233], v[206:209], v[10:13]
	v_mfma_f32_16x16x32_bf16 v[2:5], v[238:241], v[206:209], v[2:5]
	v_mfma_f32_16x16x32_bf16 v[58:61], v[234:237], v[150:153], v[58:61]
	v_mfma_f32_16x16x32_bf16 v[50:53], v[242:245], v[150:153], v[50:53]
	v_mfma_f32_16x16x32_bf16 v[42:45], v[234:237], v[186:189], v[42:45]
	v_mfma_f32_16x16x32_bf16 v[34:37], v[242:245], v[186:189], v[34:37]
	v_mfma_f32_16x16x32_bf16 v[26:29], v[234:237], v[194:197], v[26:29]
	v_mfma_f32_16x16x32_bf16 v[18:21], v[242:245], v[194:197], v[18:21]
	v_mfma_f32_16x16x32_bf16 v[10:13], v[234:237], v[216:219], v[10:13]
	v_mfma_f32_16x16x32_bf16 v[2:5], v[242:245], v[216:219], v[2:5]
	s_setprio 0
	s_barrier
	s_add_i32 s1, 0, 0x18000
	v_add_u32_e32 v142, s1, v201
	ds_read_b128 v[130:133], v142
	ds_read_b128 v[134:137], v142 offset:1024
	ds_read_b128 v[138:141], v142 offset:2048
	ds_read_b128 v[142:145], v142 offset:3072
	s_add_u32 s22, s42, 0x40000
	s_addc_u32 s23, s43, 0
	s_mov_b32 m0, s48
	v_lshl_add_u64 v[230:231], s[22:23], 0, v[158:159]
	ds_read_b128 v[146:149], v205 offset:32768
	ds_read_b128 v[150:153], v205 offset:33792
	ds_read_b128 v[182:185], v205 offset:34816
	ds_read_b128 v[186:189], v205 offset:35840
	ds_read_b128 v[190:193], v205 offset:36864
	ds_read_b128 v[194:197], v205 offset:37888
	ds_read_b128 v[206:209], v205 offset:38912
	ds_read_b128 v[216:219], v205 offset:39936
	global_load_lds_dwordx4 v[230:231], off
	v_lshl_add_u64 v[230:231], s[22:23], 0, v[156:157]
	s_mov_b32 m0, s49
	s_nop 0
	global_load_lds_dwordx4 v[230:231], off
	s_add_i32 s33, 0, 0x1c000
	v_add_u32_e32 v168, s33, v201
	ds_read_b128 v[230:233], v168
	ds_read_b128 v[234:237], v168 offset:1024
	ds_read_b128 v[238:241], v168 offset:2048
	ds_read_b128 v[242:245], v168 offset:3072
	s_waitcnt vmcnt(8)
	s_waitcnt lgkmcnt(0)
	s_barrier
	s_setprio 1
	v_mfma_f32_16x16x32_bf16 v[126:129], v[130:133], v[146:149], v[126:129]
	v_mfma_f32_16x16x32_bf16 v[118:121], v[138:141], v[146:149], v[118:121]
	v_mfma_f32_16x16x32_bf16 v[110:113], v[130:133], v[182:185], v[110:113]
	v_mfma_f32_16x16x32_bf16 v[102:105], v[138:141], v[182:185], v[102:105]
	v_mfma_f32_16x16x32_bf16 v[94:97], v[130:133], v[190:193], v[94:97]
	v_mfma_f32_16x16x32_bf16 v[86:89], v[138:141], v[190:193], v[86:89]
	v_mfma_f32_16x16x32_bf16 v[78:81], v[130:133], v[206:209], v[78:81]
	v_mfma_f32_16x16x32_bf16 v[70:73], v[138:141], v[206:209], v[70:73]
	v_mfma_f32_16x16x32_bf16 v[126:129], v[134:137], v[150:153], v[126:129]
	v_mfma_f32_16x16x32_bf16 v[118:121], v[142:145], v[150:153], v[118:121]
	v_mfma_f32_16x16x32_bf16 v[110:113], v[134:137], v[186:189], v[110:113]
	v_mfma_f32_16x16x32_bf16 v[102:105], v[142:145], v[186:189], v[102:105]
	v_mfma_f32_16x16x32_bf16 v[94:97], v[134:137], v[194:197], v[94:97]
	v_mfma_f32_16x16x32_bf16 v[86:89], v[142:145], v[194:197], v[86:89]
	v_mfma_f32_16x16x32_bf16 v[78:81], v[134:137], v[216:219], v[78:81]
	v_mfma_f32_16x16x32_bf16 v[70:73], v[142:145], v[216:219], v[70:73]
	v_mfma_f32_16x16x32_bf16 v[122:125], v[230:233], v[146:149], v[122:125]
	v_mfma_f32_16x16x32_bf16 v[114:117], v[238:241], v[146:149], v[114:117]
	v_mfma_f32_16x16x32_bf16 v[106:109], v[230:233], v[182:185], v[106:109]
	v_mfma_f32_16x16x32_bf16 v[98:101], v[238:241], v[182:185], v[98:101]
	v_mfma_f32_16x16x32_bf16 v[90:93], v[230:233], v[190:193], v[90:93]
	v_mfma_f32_16x16x32_bf16 v[82:85], v[238:241], v[190:193], v[82:85]
	v_mfma_f32_16x16x32_bf16 v[74:77], v[230:233], v[206:209], v[74:77]
	v_mfma_f32_16x16x32_bf16 v[66:69], v[238:241], v[206:209], v[66:69]
	v_mfma_f32_16x16x32_bf16 v[122:125], v[234:237], v[150:153], v[122:125]
	v_mfma_f32_16x16x32_bf16 v[114:117], v[242:245], v[150:153], v[114:117]
	v_mfma_f32_16x16x32_bf16 v[106:109], v[234:237], v[186:189], v[106:109]
	v_mfma_f32_16x16x32_bf16 v[98:101], v[242:245], v[186:189], v[98:101]
	v_mfma_f32_16x16x32_bf16 v[90:93], v[234:237], v[194:197], v[90:93]
	v_mfma_f32_16x16x32_bf16 v[82:85], v[242:245], v[194:197], v[82:85]
	v_mfma_f32_16x16x32_bf16 v[74:77], v[234:237], v[216:219], v[74:77]
	v_mfma_f32_16x16x32_bf16 v[66:69], v[242:245], v[216:219], v[66:69]
	s_setprio 0
	s_barrier
	ds_read_b128 v[146:149], v205 offset:49152
	ds_read_b128 v[150:153], v205 offset:50176
	ds_read_b128 v[182:185], v205 offset:51200
	ds_read_b128 v[186:189], v205 offset:52224
	ds_read_b128 v[190:193], v205 offset:53248
	ds_read_b128 v[194:197], v205 offset:54272
	ds_read_b128 v[206:209], v205 offset:55296
	ds_read_b128 v[216:219], v205 offset:56320
	s_add_i32 s1, s1, s17
	v_lshl_add_u64 v[176:177], v[176:177], 0, s[12:13]
	s_mov_b32 m0, s1
	s_nop 0
	global_load_lds_dwordx4 v[176:177], off
	v_lshl_add_u64 v[176:177], v[202:203], 0, s[12:13]
	s_add_i32 m0, s1, 0x2000
	s_nop 0
	global_load_lds_dwordx4 v[176:177], off
	s_mov_b32 m0, s20
	v_lshl_add_u64 v[176:177], v[220:221], 0, s[12:13]
	global_load_lds_dwordx4 v[176:177], off
	v_lshl_add_u64 v[176:177], v[246:247], 0, s[12:13]
	s_mov_b32 m0, s21
	s_nop 0
	global_load_lds_dwordx4 v[176:177], off
	s_add_u32 s22, s30, 0x40080
	s_addc_u32 s23, s31, 0
	s_add_i32 s1, s33, s17
	s_mov_b32 m0, s1
	s_nop 0
	global_load_lds_dwordx4 v0, s[22:23]
	s_add_i32 m0, s1, 0x2000
	s_nop 0
	global_load_lds_dwordx4 v154, s[22:23]
	s_waitcnt vmcnt(8)
	s_waitcnt lgkmcnt(0)
	s_barrier
	s_setprio 1
	v_mfma_f32_16x16x32_bf16 v[62:65], v[130:133], v[146:149], v[62:65]
	v_mfma_f32_16x16x32_bf16 v[54:57], v[138:141], v[146:149], v[54:57]
	v_mfma_f32_16x16x32_bf16 v[46:49], v[130:133], v[182:185], v[46:49]
	v_mfma_f32_16x16x32_bf16 v[38:41], v[138:141], v[182:185], v[38:41]
	v_mfma_f32_16x16x32_bf16 v[30:33], v[130:133], v[190:193], v[30:33]
	v_mfma_f32_16x16x32_bf16 v[22:25], v[138:141], v[190:193], v[22:25]
	v_mfma_f32_16x16x32_bf16 v[14:17], v[130:133], v[206:209], v[14:17]
	v_mfma_f32_16x16x32_bf16 v[6:9], v[138:141], v[206:209], v[6:9]
	v_mfma_f32_16x16x32_bf16 v[62:65], v[134:137], v[150:153], v[62:65]
	v_mfma_f32_16x16x32_bf16 v[54:57], v[142:145], v[150:153], v[54:57]
	v_mfma_f32_16x16x32_bf16 v[46:49], v[134:137], v[186:189], v[46:49]
	v_mfma_f32_16x16x32_bf16 v[38:41], v[142:145], v[186:189], v[38:41]
	v_mfma_f32_16x16x32_bf16 v[30:33], v[134:137], v[194:197], v[30:33]
	v_mfma_f32_16x16x32_bf16 v[22:25], v[142:145], v[194:197], v[22:25]
	v_mfma_f32_16x16x32_bf16 v[14:17], v[134:137], v[216:219], v[14:17]
	v_mfma_f32_16x16x32_bf16 v[6:9], v[142:145], v[216:219], v[6:9]
	v_mfma_f32_16x16x32_bf16 v[58:61], v[230:233], v[146:149], v[58:61]
	v_mfma_f32_16x16x32_bf16 v[50:53], v[238:241], v[146:149], v[50:53]
	v_mfma_f32_16x16x32_bf16 v[42:45], v[230:233], v[182:185], v[42:45]
	v_mfma_f32_16x16x32_bf16 v[34:37], v[238:241], v[182:185], v[34:37]
	v_mfma_f32_16x16x32_bf16 v[26:29], v[230:233], v[190:193], v[26:29]
	v_mfma_f32_16x16x32_bf16 v[18:21], v[238:241], v[190:193], v[18:21]
	v_mfma_f32_16x16x32_bf16 v[10:13], v[230:233], v[206:209], v[10:13]
	v_mfma_f32_16x16x32_bf16 v[2:5], v[238:241], v[206:209], v[2:5]
	v_mfma_f32_16x16x32_bf16 v[58:61], v[234:237], v[150:153], v[58:61]
	v_mfma_f32_16x16x32_bf16 v[50:53], v[242:245], v[150:153], v[50:53]
	v_mfma_f32_16x16x32_bf16 v[42:45], v[234:237], v[186:189], v[42:45]
	v_mfma_f32_16x16x32_bf16 v[34:37], v[242:245], v[186:189], v[34:37]
	v_mfma_f32_16x16x32_bf16 v[26:29], v[234:237], v[194:197], v[26:29]
	v_mfma_f32_16x16x32_bf16 v[18:21], v[242:245], v[194:197], v[18:21]
	v_mfma_f32_16x16x32_bf16 v[10:13], v[234:237], v[216:219], v[10:13]
	v_mfma_f32_16x16x32_bf16 v[2:5], v[242:245], v[216:219], v[2:5]
	s_setprio 0
	s_add_i32 s60, s60, 2
	s_add_u32 s28, s28, 0x100
	s_addc_u32 s29, s29, 0
	s_add_u32 s58, s58, 0x100
	s_addc_u32 s59, s59, 0
	s_cmp_gt_u32 s60, 13
	s_barrier
	s_cbranch_scc0 .LBB0_83
	s_cmpk_gt_u32 s0, 0xff
	s_cbranch_scc1 .Lrs_i2_post
	s_barrier

.LBB0_119:
	s_add_u32 s36, s36, 0x80
	s_addc_u32 s37, s37, 0
	s_add_u32 s48, s30, 0x100
	s_addc_u32 s49, s31, 0
	s_mov_b32 s22, 0
	s_waitcnt lgkmcnt(0)
	s_cmpk_gt_u32 s16, 0xff
	s_cbranch_scc0 .Lrs_i3_pre
	s_barrier
.Lrs_i3_pre:
	s_add_i32 s23, s22, 2
	s_add_u32 s1, s36, 0x80
	s_addc_u32 s30, s37, 0
	s_add_i32 s33, 0, 0x10000
	v_add_u32_e32 v142, s33, v203
	ds_read_b128 v[130:133], v142
	ds_read_b128 v[134:137], v142 offset:1024
	ds_read_b128 v[138:141], v142 offset:2048
	ds_read_b128 v[142:145], v142 offset:3072
	s_cmp_eq_u32 s69, s22
	s_cselect_b32 s31, s27, s30
	s_cselect_b32 s30, s26, s1
	s_cselect_b32 s47, s29, s49
	s_cselect_b32 s46, s28, s48
	v_lshl_add_u64 v[176:177], s[36:37], 0, v[180:181]
	s_add_i32 m0, s21, 0xc000
	ds_read_b128 v[146:149], v205
	ds_read_b128 v[150:153], v205 offset:1024
	ds_read_b128 v[154:157], v205 offset:2048
	ds_read_b128 v[184:187], v205 offset:3072
	ds_read_b128 v[188:191], v205 offset:4096
	ds_read_b128 v[192:195], v205 offset:5120
	ds_read_b128 v[196:199], v205 offset:6144
	ds_read_b128 v[206:209], v205 offset:7168
	global_load_lds_dwordx4 v[176:177], off
	v_lshl_add_u64 v[176:177], s[36:37], 0, v[182:183]
	s_add_i32 m0, s21, 0xe000
	s_nop 0
	global_load_lds_dwordx4 v[176:177], off
	s_add_i32 s1, 0, 0x14000
	v_add_u32_e32 v168, s1, v203
	ds_read_b128 v[216:219], v168
	ds_read_b128 v[230:233], v168 offset:1024
	ds_read_b128 v[234:237], v168 offset:2048
	ds_read_b128 v[238:241], v168 offset:3072
	s_waitcnt vmcnt(8)
	s_waitcnt lgkmcnt(0)
	s_barrier
	s_setprio 1
	v_mfma_f32_16x16x32_bf16 v[126:129], v[130:133], v[146:149], 0
	v_mfma_f32_16x16x32_bf16 v[122:125], v[138:141], v[146:149], 0
	v_mfma_f32_16x16x32_bf16 v[110:113], v[130:133], v[154:157], 0
	v_mfma_f32_16x16x32_bf16 v[106:109], v[138:141], v[154:157], 0
	v_mfma_f32_16x16x32_bf16 v[94:97], v[130:133], v[188:191], 0
	v_mfma_f32_16x16x32_bf16 v[90:93], v[138:141], v[188:191], 0
	v_mfma_f32_16x16x32_bf16 v[78:81], v[130:133], v[196:199], 0
	v_mfma_f32_16x16x32_bf16 v[74:77], v[138:141], v[196:199], 0
	v_mfma_f32_16x16x32_bf16 v[126:129], v[134:137], v[150:153], v[126:129]
	v_mfma_f32_16x16x32_bf16 v[122:125], v[142:145], v[150:153], v[122:125]
	v_mfma_f32_16x16x32_bf16 v[110:113], v[134:137], v[184:187], v[110:113]
	v_mfma_f32_16x16x32_bf16 v[106:109], v[142:145], v[184:187], v[106:109]
	v_mfma_f32_16x16x32_bf16 v[94:97], v[134:137], v[192:195], v[94:97]
	v_mfma_f32_16x16x32_bf16 v[90:93], v[142:145], v[192:195], v[90:93]
	v_mfma_f32_16x16x32_bf16 v[78:81], v[134:137], v[206:209], v[78:81]
	v_mfma_f32_16x16x32_bf16 v[74:77], v[142:145], v[206:209], v[74:77]
	v_mfma_f32_16x16x32_bf16 v[118:121], v[216:219], v[146:149], 0
	v_mfma_f32_16x16x32_bf16 v[114:117], v[234:237], v[146:149], 0
	v_mfma_f32_16x16x32_bf16 v[102:105], v[216:219], v[154:157], 0
	v_mfma_f32_16x16x32_bf16 v[98:101], v[234:237], v[154:157], 0
	v_mfma_f32_16x16x32_bf16 v[86:89], v[216:219], v[188:191], 0
	v_mfma_f32_16x16x32_bf16 v[82:85], v[234:237], v[188:191], 0
	v_mfma_f32_16x16x32_bf16 v[70:73], v[216:219], v[196:199], 0
	v_mfma_f32_16x16x32_bf16 v[66:69], v[234:237], v[196:199], 0
	v_mfma_f32_16x16x32_bf16 v[118:121], v[230:233], v[150:153], v[118:121]
	v_mfma_f32_16x16x32_bf16 v[114:117], v[238:241], v[150:153], v[114:117]
	v_mfma_f32_16x16x32_bf16 v[102:105], v[230:233], v[184:187], v[102:105]
	v_mfma_f32_16x16x32_bf16 v[98:101], v[238:241], v[184:187], v[98:101]
	v_mfma_f32_16x16x32_bf16 v[86:89], v[230:233], v[192:195], v[86:89]
	v_mfma_f32_16x16x32_bf16 v[82:85], v[238:241], v[192:195], v[82:85]
	v_mfma_f32_16x16x32_bf16 v[70:73], v[230:233], v[206:209], v[70:73]
	v_mfma_f32_16x16x32_bf16 v[66:69], v[238:241], v[206:209], v[66:69]
	s_setprio 0
	s_barrier
	ds_read_b128 v[146:149], v205 offset:16384
	ds_read_b128 v[150:153], v205 offset:17408
	ds_read_b128 v[154:157], v205 offset:18432
	ds_read_b128 v[184:187], v205 offset:19456
	ds_read_b128 v[188:191], v205 offset:20480
	ds_read_b128 v[192:195], v205 offset:21504
	ds_read_b128 v[196:199], v205 offset:22528
	ds_read_b128 v[206:209], v205 offset:23552
	s_add_i32 s22, s33, s20
	v_lshl_add_u64 v[176:177], s[46:47], 0, v[0:1]
	s_mov_b32 m0, s22
	s_nop 0
	global_load_lds_dwordx4 v[176:177], off
	v_lshl_add_u64 v[200:201], s[46:47], 0, v[158:159]
	s_add_i32 m0, s22, 0x2000
	s_nop 0
	global_load_lds_dwordx4 v[200:201], off
	s_mov_b32 m0, s21
	v_lshl_add_u64 v[220:221], s[30:31], 0, v[178:179]
	global_load_lds_dwordx4 v[220:221], off
	v_lshl_add_u64 v[242:243], s[30:31], 0, v[160:161]
	s_mov_b32 m0, s34
	s_nop 0
	global_load_lds_dwordx4 v[242:243], off
	s_add_u32 s46, s46, s6
	s_addc_u32 s47, s47, 0
	s_add_i32 s1, s1, s20
	v_lshl_add_u64 v[244:245], s[46:47], 0, v[0:1]
	s_mov_b32 m0, s1
	v_lshl_add_u64 v[246:247], s[46:47], 0, v[158:159]
	global_load_lds_dwordx4 v[244:245], off
	s_add_i32 m0, s1, 0x2000
	s_nop 0
	global_load_lds_dwordx4 v[246:247], off
	s_waitcnt vmcnt(8)
	s_waitcnt lgkmcnt(0)
	s_barrier
	s_setprio 1
	v_mfma_f32_16x16x32_bf16 v[62:65], v[130:133], v[146:149], 0
	v_mfma_f32_16x16x32_bf16 v[58:61], v[138:141], v[146:149], 0
	v_mfma_f32_16x16x32_bf16 v[46:49], v[130:133], v[154:157], 0
	v_mfma_f32_16x16x32_bf16 v[42:45], v[138:141], v[154:157], 0
	v_mfma_f32_16x16x32_bf16 v[30:33], v[130:133], v[188:191], 0
	v_mfma_f32_16x16x32_bf16 v[26:29], v[138:141], v[188:191], 0
	v_mfma_f32_16x16x32_bf16 v[14:17], v[130:133], v[196:199], 0
	v_mfma_f32_16x16x32_bf16 v[10:13], v[138:141], v[196:199], 0
	v_mfma_f32_16x16x32_bf16 v[62:65], v[134:137], v[150:153], v[62:65]
	v_mfma_f32_16x16x32_bf16 v[58:61], v[142:145], v[150:153], v[58:61]
	v_mfma_f32_16x16x32_bf16 v[46:49], v[134:137], v[184:187], v[46:49]
	v_mfma_f32_16x16x32_bf16 v[42:45], v[142:145], v[184:187], v[42:45]
	v_mfma_f32_16x16x32_bf16 v[30:33], v[134:137], v[192:195], v[30:33]
	v_mfma_f32_16x16x32_bf16 v[26:29], v[142:145], v[192:195], v[26:29]
	v_mfma_f32_16x16x32_bf16 v[14:17], v[134:137], v[206:209], v[14:17]
	v_mfma_f32_16x16x32_bf16 v[10:13], v[142:145], v[206:209], v[10:13]
	v_mfma_f32_16x16x32_bf16 v[54:57], v[216:219], v[146:149], 0
	v_mfma_f32_16x16x32_bf16 v[50:53], v[234:237], v[146:149], 0
	v_mfma_f32_16x16x32_bf16 v[38:41], v[216:219], v[154:157], 0
	v_mfma_f32_16x16x32_bf16 v[34:37], v[234:237], v[154:157], 0
	v_mfma_f32_16x16x32_bf16 v[22:25], v[216:219], v[188:191], 0
	v_mfma_f32_16x16x32_bf16 v[18:21], v[234:237], v[188:191], 0
	v_mfma_f32_16x16x32_bf16 v[6:9], v[216:219], v[196:199], 0
	v_mfma_f32_16x16x32_bf16 v[2:5], v[234:237], v[196:199], 0
	v_mfma_f32_16x16x32_bf16 v[54:57], v[230:233], v[150:153], v[54:57]
	v_mfma_f32_16x16x32_bf16 v[50:53], v[238:241], v[150:153], v[50:53]
	v_mfma_f32_16x16x32_bf16 v[38:41], v[230:233], v[184:187], v[38:41]
	v_mfma_f32_16x16x32_bf16 v[34:37], v[238:241], v[184:187], v[34:37]
	v_mfma_f32_16x16x32_bf16 v[22:25], v[230:233], v[192:195], v[22:25]
	v_mfma_f32_16x16x32_bf16 v[18:21], v[238:241], v[192:195], v[18:21]
	v_mfma_f32_16x16x32_bf16 v[6:9], v[230:233], v[206:209], v[6:9]
	v_mfma_f32_16x16x32_bf16 v[2:5], v[238:241], v[206:209], v[2:5]
	s_setprio 0
	s_barrier
	s_add_i32 s1, 0, 0x18000
	v_add_u32_e32 v142, s1, v203
	ds_read_b128 v[130:133], v142
	ds_read_b128 v[134:137], v142 offset:1024
	ds_read_b128 v[138:141], v142 offset:2048
	ds_read_b128 v[142:145], v142 offset:3072
	s_add_u32 s30, s30, s6
	s_addc_u32 s31, s31, 0
	s_mov_b32 m0, s63
	v_lshl_add_u64 v[216:217], s[30:31], 0, v[178:179]
	ds_read_b128 v[146:149], v205 offset:32768
	ds_read_b128 v[150:153], v205 offset:33792
	ds_read_b128 v[154:157], v205 offset:34816
	ds_read_b128 v[184:187], v205 offset:35840
	ds_read_b128 v[188:191], v205 offset:36864
	ds_read_b128 v[192:195], v205 offset:37888
	ds_read_b128 v[196:199], v205 offset:38912
	ds_read_b128 v[206:209], v205 offset:39936
	global_load_lds_dwordx4 v[216:217], off
	v_lshl_add_u64 v[216:217], s[30:31], 0, v[160:161]
	s_mov_b32 m0, s64
	s_nop 0
	global_load_lds_dwordx4 v[216:217], off
	s_add_i32 s22, 0, 0x1c000
	v_add_u32_e32 v168, s22, v203
	ds_read_b128 v[216:219], v168
	ds_read_b128 v[230:233], v168 offset:1024
	ds_read_b128 v[234:237], v168 offset:2048
	ds_read_b128 v[238:241], v168 offset:3072
	s_waitcnt vmcnt(8)
	s_waitcnt lgkmcnt(0)
	s_barrier
	s_setprio 1
	v_mfma_f32_16x16x32_bf16 v[126:129], v[130:133], v[146:149], v[126:129]
	v_mfma_f32_16x16x32_bf16 v[122:125], v[138:141], v[146:149], v[122:125]
	v_mfma_f32_16x16x32_bf16 v[110:113], v[130:133], v[154:157], v[110:113]
	v_mfma_f32_16x16x32_bf16 v[106:109], v[138:141], v[154:157], v[106:109]
	v_mfma_f32_16x16x32_bf16 v[94:97], v[130:133], v[188:191], v[94:97]
	v_mfma_f32_16x16x32_bf16 v[90:93], v[138:141], v[188:191], v[90:93]
	v_mfma_f32_16x16x32_bf16 v[78:81], v[130:133], v[196:199], v[78:81]
	v_mfma_f32_16x16x32_bf16 v[74:77], v[138:141], v[196:199], v[74:77]
	v_mfma_f32_16x16x32_bf16 v[126:129], v[134:137], v[150:153], v[126:129]
	v_mfma_f32_16x16x32_bf16 v[122:125], v[142:145], v[150:153], v[122:125]
	v_mfma_f32_16x16x32_bf16 v[110:113], v[134:137], v[184:187], v[110:113]
	v_mfma_f32_16x16x32_bf16 v[106:109], v[142:145], v[184:187], v[106:109]
	v_mfma_f32_16x16x32_bf16 v[94:97], v[134:137], v[192:195], v[94:97]
	v_mfma_f32_16x16x32_bf16 v[90:93], v[142:145], v[192:195], v[90:93]
	v_mfma_f32_16x16x32_bf16 v[78:81], v[134:137], v[206:209], v[78:81]
	v_mfma_f32_16x16x32_bf16 v[74:77], v[142:145], v[206:209], v[74:77]
	v_mfma_f32_16x16x32_bf16 v[118:121], v[216:219], v[146:149], v[118:121]
	v_mfma_f32_16x16x32_bf16 v[114:117], v[234:237], v[146:149], v[114:117]
	v_mfma_f32_16x16x32_bf16 v[102:105], v[216:219], v[154:157], v[102:105]
	v_mfma_f32_16x16x32_bf16 v[98:101], v[234:237], v[154:157], v[98:101]
	v_mfma_f32_16x16x32_bf16 v[86:89], v[216:219], v[188:191], v[86:89]
	v_mfma_f32_16x16x32_bf16 v[82:85], v[234:237], v[188:191], v[82:85]
	v_mfma_f32_16x16x32_bf16 v[70:73], v[216:219], v[196:199], v[70:73]
	v_mfma_f32_16x16x32_bf16 v[66:69], v[234:237], v[196:199], v[66:69]
	v_mfma_f32_16x16x32_bf16 v[118:121], v[230:233], v[150:153], v[118:121]
	v_mfma_f32_16x16x32_bf16 v[114:117], v[238:241], v[150:153], v[114:117]
	v_mfma_f32_16x16x32_bf16 v[102:105], v[230:233], v[184:187], v[102:105]
	v_mfma_f32_16x16x32_bf16 v[98:101], v[238:241], v[184:187], v[98:101]
	v_mfma_f32_16x16x32_bf16 v[86:89], v[230:233], v[192:195], v[86:89]
	v_mfma_f32_16x16x32_bf16 v[82:85], v[238:241], v[192:195], v[82:85]
	v_mfma_f32_16x16x32_bf16 v[70:73], v[230:233], v[206:209], v[70:73]
	v_mfma_f32_16x16x32_bf16 v[66:69], v[238:241], v[206:209], v[66:69]
	s_setprio 0
	s_barrier
	ds_read_b128 v[146:149], v205 offset:49152
	ds_read_b128 v[150:153], v205 offset:50176
	ds_read_b128 v[154:157], v205 offset:51200
	ds_read_b128 v[184:187], v205 offset:52224
	ds_read_b128 v[188:191], v205 offset:53248
	ds_read_b128 v[192:195], v205 offset:54272
	ds_read_b128 v[196:199], v205 offset:55296
	ds_read_b128 v[206:209], v205 offset:56320
	s_add_i32 s1, s1, s20
	v_lshl_add_u64 v[176:177], v[176:177], 0, s[12:13]
	s_mov_b32 m0, s1
	s_nop 0
	global_load_lds_dwordx4 v[176:177], off
	v_lshl_add_u64 v[176:177], v[200:201], 0, s[12:13]
	s_add_i32 m0, s1, 0x2000
	s_nop 0
	global_load_lds_dwordx4 v[176:177], off
	s_mov_b32 m0, s65
	v_lshl_add_u64 v[176:177], v[220:221], 0, s[12:13]
	global_load_lds_dwordx4 v[176:177], off
	v_lshl_add_u64 v[176:177], v[242:243], 0, s[12:13]
	s_mov_b32 m0, s66
	s_nop 0
	global_load_lds_dwordx4 v[176:177], off
	s_add_i32 s1, s22, s20
	v_lshl_add_u64 v[176:177], v[244:245], 0, s[12:13]
	s_mov_b32 m0, s1
	s_nop 0
	global_load_lds_dwordx4 v[176:177], off
	v_lshl_add_u64 v[176:177], v[246:247], 0, s[12:13]
	s_add_i32 m0, s1, 0x2000
	s_nop 0
	global_load_lds_dwordx4 v[176:177], off
	s_waitcnt vmcnt(8)
	s_waitcnt lgkmcnt(0)
	s_barrier
	s_setprio 1
	v_mfma_f32_16x16x32_bf16 v[62:65], v[130:133], v[146:149], v[62:65]
	v_mfma_f32_16x16x32_bf16 v[58:61], v[138:141], v[146:149], v[58:61]
	v_mfma_f32_16x16x32_bf16 v[46:49], v[130:133], v[154:157], v[46:49]
	v_mfma_f32_16x16x32_bf16 v[42:45], v[138:141], v[154:157], v[42:45]
	v_mfma_f32_16x16x32_bf16 v[30:33], v[130:133], v[188:191], v[30:33]
	v_mfma_f32_16x16x32_bf16 v[26:29], v[138:141], v[188:191], v[26:29]
	v_mfma_f32_16x16x32_bf16 v[14:17], v[130:133], v[196:199], v[14:17]
	v_mfma_f32_16x16x32_bf16 v[10:13], v[138:141], v[196:199], v[10:13]
	v_mfma_f32_16x16x32_bf16 v[62:65], v[134:137], v[150:153], v[62:65]
	v_mfma_f32_16x16x32_bf16 v[58:61], v[142:145], v[150:153], v[58:61]
	v_mfma_f32_16x16x32_bf16 v[46:49], v[134:137], v[184:187], v[46:49]
	v_mfma_f32_16x16x32_bf16 v[42:45], v[142:145], v[184:187], v[42:45]
	v_mfma_f32_16x16x32_bf16 v[30:33], v[134:137], v[192:195], v[30:33]
	v_mfma_f32_16x16x32_bf16 v[26:29], v[142:145], v[192:195], v[26:29]
	v_mfma_f32_16x16x32_bf16 v[14:17], v[134:137], v[206:209], v[14:17]
	v_mfma_f32_16x16x32_bf16 v[10:13], v[142:145], v[206:209], v[10:13]
	v_mfma_f32_16x16x32_bf16 v[54:57], v[216:219], v[146:149], v[54:57]
	v_mfma_f32_16x16x32_bf16 v[50:53], v[234:237], v[146:149], v[50:53]
	v_mfma_f32_16x16x32_bf16 v[38:41], v[216:219], v[154:157], v[38:41]
	v_mfma_f32_16x16x32_bf16 v[34:37], v[234:237], v[154:157], v[34:37]
	v_mfma_f32_16x16x32_bf16 v[22:25], v[216:219], v[188:191], v[22:25]
	v_mfma_f32_16x16x32_bf16 v[18:21], v[234:237], v[188:191], v[18:21]
	v_mfma_f32_16x16x32_bf16 v[6:9], v[216:219], v[196:199], v[6:9]
	v_mfma_f32_16x16x32_bf16 v[2:5], v[234:237], v[196:199], v[2:5]
	v_mfma_f32_16x16x32_bf16 v[54:57], v[230:233], v[150:153], v[54:57]
	v_mfma_f32_16x16x32_bf16 v[50:53], v[238:241], v[150:153], v[50:53]
	v_mfma_f32_16x16x32_bf16 v[38:41], v[230:233], v[184:187], v[38:41]
	v_mfma_f32_16x16x32_bf16 v[34:37], v[238:241], v[184:187], v[34:37]
	v_mfma_f32_16x16x32_bf16 v[22:25], v[230:233], v[192:195], v[22:25]
	v_mfma_f32_16x16x32_bf16 v[18:21], v[238:241], v[192:195], v[18:21]
	v_mfma_f32_16x16x32_bf16 v[6:9], v[230:233], v[206:209], v[6:9]
	v_mfma_f32_16x16x32_bf16 v[2:5], v[238:241], v[206:209], v[2:5]
	s_setprio 0
	s_add_u32 s36, s36, 0x100
	s_addc_u32 s37, s37, 0
	s_add_u32 s48, s48, 0x100
	s_addc_u32 s49, s49, 0
	s_cmp_ge_u32 s23, s68
	s_mov_b32 s22, s23
	s_barrier

.Lrs_i4_pre:
	s_add_i32 s23, s22, 2
	s_add_u32 s1, s36, 0x80
	s_addc_u32 s30, s37, 0
	s_add_i32 s33, 0, 0x10000
	v_add_u32_e32 v142, s33, v181
	ds_read_b128 v[130:133], v142
	ds_read_b128 v[134:137], v142 offset:1024
	ds_read_b128 v[138:141], v142 offset:2048
	ds_read_b128 v[142:145], v142 offset:3072
	s_cmp_eq_u32 s68, s22
	s_cselect_b32 s31, s27, s30
	s_cselect_b32 s30, s26, s1
	s_cselect_b32 s47, s29, s49
	s_cselect_b32 s46, s28, s48
	v_lshl_add_u64 v[160:161], s[36:37], 0, v[152:153]
	s_add_i32 m0, s21, 0xc000
	ds_read_b128 v[156:159], v183
	ds_read_b128 v[184:187], v183 offset:1024
	ds_read_b128 v[188:191], v183 offset:2048
	ds_read_b128 v[192:195], v183 offset:3072
	ds_read_b128 v[196:199], v183 offset:4096
	ds_read_b128 v[200:203], v183 offset:5120
	ds_read_b128 v[204:207], v183 offset:6144
	ds_read_b128 v[216:219], v183 offset:7168
	global_load_lds_dwordx4 v[160:161], off
	v_lshl_add_u64 v[160:161], s[36:37], 0, v[154:155]
	s_add_i32 m0, s21, 0xe000
	s_nop 0
	global_load_lds_dwordx4 v[160:161], off
	s_add_i32 s1, 0, 0x14000
	v_add_u32_e32 v160, s1, v181
	ds_read_b128 v[230:233], v160
	ds_read_b128 v[234:237], v160 offset:1024
	ds_read_b128 v[238:241], v160 offset:2048
	ds_read_b128 v[242:245], v160 offset:3072
	s_waitcnt vmcnt(8)
	s_waitcnt lgkmcnt(0)
	s_barrier
	s_setprio 1
	v_mfma_f32_16x16x32_bf16 v[126:129], v[130:133], v[156:159], 0
	v_mfma_f32_16x16x32_bf16 v[122:125], v[138:141], v[156:159], 0
	v_mfma_f32_16x16x32_bf16 v[110:113], v[130:133], v[188:191], 0
	v_mfma_f32_16x16x32_bf16 v[106:109], v[138:141], v[188:191], 0
	v_mfma_f32_16x16x32_bf16 v[94:97], v[130:133], v[196:199], 0
	v_mfma_f32_16x16x32_bf16 v[90:93], v[138:141], v[196:199], 0
	v_mfma_f32_16x16x32_bf16 v[78:81], v[130:133], v[204:207], 0
	v_mfma_f32_16x16x32_bf16 v[74:77], v[138:141], v[204:207], 0
	v_mfma_f32_16x16x32_bf16 v[126:129], v[134:137], v[184:187], v[126:129]
	v_mfma_f32_16x16x32_bf16 v[122:125], v[142:145], v[184:187], v[122:125]
	v_mfma_f32_16x16x32_bf16 v[110:113], v[134:137], v[192:195], v[110:113]
	v_mfma_f32_16x16x32_bf16 v[106:109], v[142:145], v[192:195], v[106:109]
	v_mfma_f32_16x16x32_bf16 v[94:97], v[134:137], v[200:203], v[94:97]
	v_mfma_f32_16x16x32_bf16 v[90:93], v[142:145], v[200:203], v[90:93]
	v_mfma_f32_16x16x32_bf16 v[78:81], v[134:137], v[216:219], v[78:81]
	v_mfma_f32_16x16x32_bf16 v[74:77], v[142:145], v[216:219], v[74:77]
	v_mfma_f32_16x16x32_bf16 v[118:121], v[230:233], v[156:159], 0
	v_mfma_f32_16x16x32_bf16 v[114:117], v[238:241], v[156:159], 0
	v_mfma_f32_16x16x32_bf16 v[102:105], v[230:233], v[188:191], 0
	v_mfma_f32_16x16x32_bf16 v[98:101], v[238:241], v[188:191], 0
	v_mfma_f32_16x16x32_bf16 v[86:89], v[230:233], v[196:199], 0
	v_mfma_f32_16x16x32_bf16 v[82:85], v[238:241], v[196:199], 0
	v_mfma_f32_16x16x32_bf16 v[70:73], v[230:233], v[204:207], 0
	v_mfma_f32_16x16x32_bf16 v[66:69], v[238:241], v[204:207], 0
	v_mfma_f32_16x16x32_bf16 v[118:121], v[234:237], v[184:187], v[118:121]
	v_mfma_f32_16x16x32_bf16 v[114:117], v[242:245], v[184:187], v[114:117]
	v_mfma_f32_16x16x32_bf16 v[102:105], v[234:237], v[192:195], v[102:105]
	v_mfma_f32_16x16x32_bf16 v[98:101], v[242:245], v[192:195], v[98:101]
	v_mfma_f32_16x16x32_bf16 v[86:89], v[234:237], v[200:203], v[86:89]
	v_mfma_f32_16x16x32_bf16 v[82:85], v[242:245], v[200:203], v[82:85]
	v_mfma_f32_16x16x32_bf16 v[70:73], v[234:237], v[216:219], v[70:73]
	v_mfma_f32_16x16x32_bf16 v[66:69], v[242:245], v[216:219], v[66:69]
	s_setprio 0
	s_barrier
	ds_read_b128 v[156:159], v183 offset:16384
	ds_read_b128 v[184:187], v183 offset:17408
	ds_read_b128 v[188:191], v183 offset:18432
	ds_read_b128 v[192:195], v183 offset:19456
	ds_read_b128 v[196:199], v183 offset:20480
	ds_read_b128 v[200:203], v183 offset:21504
	ds_read_b128 v[204:207], v183 offset:22528
	ds_read_b128 v[216:219], v183 offset:23552
	s_add_i32 s22, s33, s20
	v_lshl_add_u64 v[160:161], s[46:47], 0, v[0:1]
	s_mov_b32 m0, s22
	v_lshl_add_u64 v[176:177], s[46:47], 0, v[146:147]
	global_load_lds_dwordx4 v[160:161], off
	s_add_i32 m0, s22, 0x2000
	s_nop 0
	global_load_lds_dwordx4 v[176:177], off
	s_mov_b32 m0, s21
	v_lshl_add_u64 v[178:179], s[30:31], 0, v[150:151]
	global_load_lds_dwordx4 v[178:179], off
	v_lshl_add_u64 v[208:209], s[30:31], 0, v[148:149]
	s_mov_b32 m0, s34
	s_nop 0
	global_load_lds_dwordx4 v[208:209], off
	s_add_u32 s46, s46, s6
	s_addc_u32 s47, s47, 0
	s_add_i32 s1, s1, s20
	v_lshl_add_u64 v[220:221], s[46:47], 0, v[0:1]
	s_mov_b32 m0, s1
	v_lshl_add_u64 v[246:247], s[46:47], 0, v[146:147]
	global_load_lds_dwordx4 v[220:221], off
	s_add_i32 m0, s1, 0x2000
	s_nop 0
	global_load_lds_dwordx4 v[246:247], off
	s_waitcnt vmcnt(8)
	s_waitcnt lgkmcnt(0)
	s_barrier
	s_setprio 1
	v_mfma_f32_16x16x32_bf16 v[62:65], v[130:133], v[156:159], 0
	v_mfma_f32_16x16x32_bf16 v[58:61], v[138:141], v[156:159], 0
	v_mfma_f32_16x16x32_bf16 v[46:49], v[130:133], v[188:191], 0
	v_mfma_f32_16x16x32_bf16 v[42:45], v[138:141], v[188:191], 0
	v_mfma_f32_16x16x32_bf16 v[30:33], v[130:133], v[196:199], 0
	v_mfma_f32_16x16x32_bf16 v[26:29], v[138:141], v[196:199], 0
	v_mfma_f32_16x16x32_bf16 v[14:17], v[130:133], v[204:207], 0
	v_mfma_f32_16x16x32_bf16 v[10:13], v[138:141], v[204:207], 0
	v_mfma_f32_16x16x32_bf16 v[62:65], v[134:137], v[184:187], v[62:65]
	v_mfma_f32_16x16x32_bf16 v[58:61], v[142:145], v[184:187], v[58:61]
	v_mfma_f32_16x16x32_bf16 v[46:49], v[134:137], v[192:195], v[46:49]
	v_mfma_f32_16x16x32_bf16 v[42:45], v[142:145], v[192:195], v[42:45]
	v_mfma_f32_16x16x32_bf16 v[30:33], v[134:137], v[200:203], v[30:33]
	v_mfma_f32_16x16x32_bf16 v[26:29], v[142:145], v[200:203], v[26:29]
	v_mfma_f32_16x16x32_bf16 v[14:17], v[134:137], v[216:219], v[14:17]
	v_mfma_f32_16x16x32_bf16 v[10:13], v[142:145], v[216:219], v[10:13]
	v_mfma_f32_16x16x32_bf16 v[54:57], v[230:233], v[156:159], 0
	v_mfma_f32_16x16x32_bf16 v[50:53], v[238:241], v[156:159], 0
	v_mfma_f32_16x16x32_bf16 v[38:41], v[230:233], v[188:191], 0
	v_mfma_f32_16x16x32_bf16 v[34:37], v[238:241], v[188:191], 0
	v_mfma_f32_16x16x32_bf16 v[22:25], v[230:233], v[196:199], 0
	v_mfma_f32_16x16x32_bf16 v[18:21], v[238:241], v[196:199], 0
	v_mfma_f32_16x16x32_bf16 v[6:9], v[230:233], v[204:207], 0
	v_mfma_f32_16x16x32_bf16 v[2:5], v[238:241], v[204:207], 0
	v_mfma_f32_16x16x32_bf16 v[54:57], v[234:237], v[184:187], v[54:57]
	v_mfma_f32_16x16x32_bf16 v[50:53], v[242:245], v[184:187], v[50:53]
	v_mfma_f32_16x16x32_bf16 v[38:41], v[234:237], v[192:195], v[38:41]
	v_mfma_f32_16x16x32_bf16 v[34:37], v[242:245], v[192:195], v[34:37]
	v_mfma_f32_16x16x32_bf16 v[22:25], v[234:237], v[200:203], v[22:25]
	v_mfma_f32_16x16x32_bf16 v[18:21], v[242:245], v[200:203], v[18:21]
	v_mfma_f32_16x16x32_bf16 v[6:9], v[234:237], v[216:219], v[6:9]
	v_mfma_f32_16x16x32_bf16 v[2:5], v[242:245], v[216:219], v[2:5]
	s_setprio 0
	s_barrier
	s_add_i32 s1, 0, 0x18000
	v_add_u32_e32 v142, s1, v181
	ds_read_b128 v[130:133], v142
	ds_read_b128 v[134:137], v142 offset:1024
	ds_read_b128 v[138:141], v142 offset:2048
	ds_read_b128 v[142:145], v142 offset:3072
	s_add_u32 s30, s30, s6
	s_addc_u32 s31, s31, 0
	s_mov_b32 m0, s63
	v_lshl_add_u64 v[230:231], s[30:31], 0, v[150:151]
	ds_read_b128 v[156:159], v183 offset:32768
	ds_read_b128 v[184:187], v183 offset:33792
	ds_read_b128 v[188:191], v183 offset:34816
	ds_read_b128 v[192:195], v183 offset:35840
	ds_read_b128 v[196:199], v183 offset:36864
	ds_read_b128 v[200:203], v183 offset:37888
	ds_read_b128 v[204:207], v183 offset:38912
	ds_read_b128 v[216:219], v183 offset:39936
	global_load_lds_dwordx4 v[230:231], off
	v_lshl_add_u64 v[230:231], s[30:31], 0, v[148:149]
	s_mov_b32 m0, s64
	s_nop 0
	global_load_lds_dwordx4 v[230:231], off
	s_add_i32 s22, 0, 0x1c000
	v_add_u32_e32 v168, s22, v181
	ds_read_b128 v[230:233], v168
	ds_read_b128 v[234:237], v168 offset:1024
	ds_read_b128 v[238:241], v168 offset:2048
	ds_read_b128 v[242:245], v168 offset:3072
	s_waitcnt vmcnt(8)
	s_waitcnt lgkmcnt(0)
	s_barrier
	s_setprio 1
	v_mfma_f32_16x16x32_bf16 v[126:129], v[130:133], v[156:159], v[126:129]
	v_mfma_f32_16x16x32_bf16 v[122:125], v[138:141], v[156:159], v[122:125]
	v_mfma_f32_16x16x32_bf16 v[110:113], v[130:133], v[188:191], v[110:113]
	v_mfma_f32_16x16x32_bf16 v[106:109], v[138:141], v[188:191], v[106:109]
	v_mfma_f32_16x16x32_bf16 v[94:97], v[130:133], v[196:199], v[94:97]
	v_mfma_f32_16x16x32_bf16 v[90:93], v[138:141], v[196:199], v[90:93]
	v_mfma_f32_16x16x32_bf16 v[78:81], v[130:133], v[204:207], v[78:81]
	v_mfma_f32_16x16x32_bf16 v[74:77], v[138:141], v[204:207], v[74:77]
	v_mfma_f32_16x16x32_bf16 v[126:129], v[134:137], v[184:187], v[126:129]
	v_mfma_f32_16x16x32_bf16 v[122:125], v[142:145], v[184:187], v[122:125]
	v_mfma_f32_16x16x32_bf16 v[110:113], v[134:137], v[192:195], v[110:113]
	v_mfma_f32_16x16x32_bf16 v[106:109], v[142:145], v[192:195], v[106:109]
	v_mfma_f32_16x16x32_bf16 v[94:97], v[134:137], v[200:203], v[94:97]
	v_mfma_f32_16x16x32_bf16 v[90:93], v[142:145], v[200:203], v[90:93]
	v_mfma_f32_16x16x32_bf16 v[78:81], v[134:137], v[216:219], v[78:81]
	v_mfma_f32_16x16x32_bf16 v[74:77], v[142:145], v[216:219], v[74:77]
	v_mfma_f32_16x16x32_bf16 v[118:121], v[230:233], v[156:159], v[118:121]
	v_mfma_f32_16x16x32_bf16 v[114:117], v[238:241], v[156:159], v[114:117]
	v_mfma_f32_16x16x32_bf16 v[102:105], v[230:233], v[188:191], v[102:105]
	v_mfma_f32_16x16x32_bf16 v[98:101], v[238:241], v[188:191], v[98:101]
	v_mfma_f32_16x16x32_bf16 v[86:89], v[230:233], v[196:199], v[86:89]
	v_mfma_f32_16x16x32_bf16 v[82:85], v[238:241], v[196:199], v[82:85]
	v_mfma_f32_16x16x32_bf16 v[70:73], v[230:233], v[204:207], v[70:73]
	v_mfma_f32_16x16x32_bf16 v[66:69], v[238:241], v[204:207], v[66:69]
	v_mfma_f32_16x16x32_bf16 v[118:121], v[234:237], v[184:187], v[118:121]
	v_mfma_f32_16x16x32_bf16 v[114:117], v[242:245], v[184:187], v[114:117]
	v_mfma_f32_16x16x32_bf16 v[102:105], v[234:237], v[192:195], v[102:105]
	v_mfma_f32_16x16x32_bf16 v[98:101], v[242:245], v[192:195], v[98:101]
	v_mfma_f32_16x16x32_bf16 v[86:89], v[234:237], v[200:203], v[86:89]
	v_mfma_f32_16x16x32_bf16 v[82:85], v[242:245], v[200:203], v[82:85]
	v_mfma_f32_16x16x32_bf16 v[70:73], v[234:237], v[216:219], v[70:73]
	v_mfma_f32_16x16x32_bf16 v[66:69], v[242:245], v[216:219], v[66:69]
	s_setprio 0
	s_barrier
	ds_read_b128 v[156:159], v183 offset:49152
	ds_read_b128 v[184:187], v183 offset:50176
	ds_read_b128 v[188:191], v183 offset:51200
	ds_read_b128 v[192:195], v183 offset:52224
	ds_read_b128 v[196:199], v183 offset:53248
	ds_read_b128 v[200:203], v183 offset:54272
	ds_read_b128 v[204:207], v183 offset:55296
	ds_read_b128 v[216:219], v183 offset:56320
	s_add_i32 s1, s1, s20
	v_lshl_add_u64 v[160:161], v[160:161], 0, s[12:13]
	s_mov_b32 m0, s1
	s_nop 0
	global_load_lds_dwordx4 v[160:161], off
	v_lshl_add_u64 v[160:161], v[176:177], 0, s[12:13]
	s_add_i32 m0, s1, 0x2000
	s_nop 0
	global_load_lds_dwordx4 v[160:161], off
	s_mov_b32 m0, s65
	v_lshl_add_u64 v[160:161], v[178:179], 0, s[12:13]
	global_load_lds_dwordx4 v[160:161], off
	v_lshl_add_u64 v[160:161], v[208:209], 0, s[12:13]
	s_mov_b32 m0, s66
	s_nop 0
	global_load_lds_dwordx4 v[160:161], off
	s_add_i32 s1, s22, s20
	v_lshl_add_u64 v[160:161], v[220:221], 0, s[12:13]
	s_mov_b32 m0, s1
	s_nop 0
	global_load_lds_dwordx4 v[160:161], off
	v_lshl_add_u64 v[160:161], v[246:247], 0, s[12:13]
	s_add_i32 m0, s1, 0x2000
	s_nop 0
	global_load_lds_dwordx4 v[160:161], off
	s_waitcnt vmcnt(8)
	s_waitcnt lgkmcnt(0)
	s_barrier
	s_setprio 1
	v_mfma_f32_16x16x32_bf16 v[62:65], v[130:133], v[156:159], v[62:65]
	v_mfma_f32_16x16x32_bf16 v[58:61], v[138:141], v[156:159], v[58:61]
	v_mfma_f32_16x16x32_bf16 v[46:49], v[130:133], v[188:191], v[46:49]
	v_mfma_f32_16x16x32_bf16 v[42:45], v[138:141], v[188:191], v[42:45]
	v_mfma_f32_16x16x32_bf16 v[30:33], v[130:133], v[196:199], v[30:33]
	v_mfma_f32_16x16x32_bf16 v[26:29], v[138:141], v[196:199], v[26:29]
	v_mfma_f32_16x16x32_bf16 v[14:17], v[130:133], v[204:207], v[14:17]
	v_mfma_f32_16x16x32_bf16 v[10:13], v[138:141], v[204:207], v[10:13]
	v_mfma_f32_16x16x32_bf16 v[62:65], v[134:137], v[184:187], v[62:65]
	v_mfma_f32_16x16x32_bf16 v[58:61], v[142:145], v[184:187], v[58:61]
	v_mfma_f32_16x16x32_bf16 v[46:49], v[134:137], v[192:195], v[46:49]
	v_mfma_f32_16x16x32_bf16 v[42:45], v[142:145], v[192:195], v[42:45]
	v_mfma_f32_16x16x32_bf16 v[30:33], v[134:137], v[200:203], v[30:33]
	v_mfma_f32_16x16x32_bf16 v[26:29], v[142:145], v[200:203], v[26:29]
	v_mfma_f32_16x16x32_bf16 v[14:17], v[134:137], v[216:219], v[14:17]
	v_mfma_f32_16x16x32_bf16 v[10:13], v[142:145], v[216:219], v[10:13]
	v_mfma_f32_16x16x32_bf16 v[54:57], v[230:233], v[156:159], v[54:57]
	v_mfma_f32_16x16x32_bf16 v[50:53], v[238:241], v[156:159], v[50:53]
	v_mfma_f32_16x16x32_bf16 v[38:41], v[230:233], v[188:191], v[38:41]
	v_mfma_f32_16x16x32_bf16 v[34:37], v[238:241], v[188:191], v[34:37]
	v_mfma_f32_16x16x32_bf16 v[22:25], v[230:233], v[196:199], v[22:25]
	v_mfma_f32_16x16x32_bf16 v[18:21], v[238:241], v[196:199], v[18:21]
	v_mfma_f32_16x16x32_bf16 v[6:9], v[230:233], v[204:207], v[6:9]
	v_mfma_f32_16x16x32_bf16 v[2:5], v[238:241], v[204:207], v[2:5]
	v_mfma_f32_16x16x32_bf16 v[54:57], v[234:237], v[184:187], v[54:57]
	v_mfma_f32_16x16x32_bf16 v[50:53], v[242:245], v[184:187], v[50:53]
	v_mfma_f32_16x16x32_bf16 v[38:41], v[234:237], v[192:195], v[38:41]
	v_mfma_f32_16x16x32_bf16 v[34:37], v[242:245], v[192:195], v[34:37]
	v_mfma_f32_16x16x32_bf16 v[22:25], v[234:237], v[200:203], v[22:25]
	v_mfma_f32_16x16x32_bf16 v[18:21], v[242:245], v[200:203], v[18:21]
	v_mfma_f32_16x16x32_bf16 v[6:9], v[234:237], v[216:219], v[6:9]
	v_mfma_f32_16x16x32_bf16 v[2:5], v[242:245], v[216:219], v[2:5]
	s_setprio 0
	s_add_u32 s36, s36, 0x100
	s_addc_u32 s37, s37, 0
	s_add_u32 s48, s48, 0x100
	s_addc_u32 s49, s49, 0
	s_cmp_ge_u32 s23, s0
	s_mov_b32 s22, s23
	s_barrier

.LBB0_206:
	s_and_b64 vcc, exec, s[56:57]
	s_cbranch_vccnz .LBB0_307
	s_branch .LBB0_375
.Lfar_end:
	s_branch .LBB0_623
.LBB0_207:
	v_readlane_b32 s50, v254, 42
	v_readlane_b32 s51, v254, 43
	s_and_b64 vcc, exec, s[56:57]
	s_cbranch_vccnz .LBB0_307
	s_branch .LBB0_375

.LBB0_288:
	s_ashr_i32 s27, s26, 31
	s_lshl_b64 s[22:23], s[26:27], 19
	v_cmp_lt_i64_e32 vcc, s[28:29], v[170:171]
	s_add_u32 s28, s96, s22
	s_addc_u32 s29, s97, s23
	s_and_b64 s[22:23], vcc, exec
	s_cselect_b32 s27, s29, s43
	s_cselect_b32 s50, s28, s42
	s_ashr_i32 s7, s6, 31
	s_lshl_b64 s[22:23], s[6:7], 19
	s_add_u32 s36, s10, s22
	s_addc_u32 s37, s11, s23
	s_and_b64 s[22:23], vcc, exec
	s_cselect_b32 s7, s37, s31
	s_cselect_b32 s51, s36, s30
	s_add_u32 s42, s42, 0x40080
	s_addc_u32 s43, s43, 0
	s_add_u32 s52, s30, 0x100
	s_addc_u32 s53, s31, 0
	s_mov_b32 s54, -2
	s_cmpk_gt_u32 s0, 0xff
	s_cbranch_scc0 .Lrs_proj0_pre
	s_barrier
.Lrs_proj0_pre:
	s_add_u32 s1, s42, 0xfffc0080
	s_addc_u32 s22, s43, -1
	s_add_i32 s23, 0, 0x10000
	v_add_u32_e32 v142, s23, v217
	ds_read_b128 v[130:133], v142
	ds_read_b128 v[134:137], v142 offset:1024
	ds_read_b128 v[138:141], v142 offset:2048
	ds_read_b128 v[142:145], v142 offset:3072
	s_cmp_eq_u32 s54, 12
	s_cselect_b32 s45, s27, s22
	s_cselect_b32 s44, s50, s1
	s_cselect_b32 s31, s7, s53
	s_cselect_b32 s30, s51, s52
	v_lshl_add_u64 v[176:177], s[42:43], 0, v[190:191]
	s_add_i32 m0, s16, 0xc000
	ds_read_b128 v[146:149], v219
	ds_read_b128 v[150:153], v219 offset:1024
	ds_read_b128 v[154:157], v219 offset:2048
	ds_read_b128 v[158:161], v219 offset:3072
	ds_read_b128 v[194:197], v219 offset:4096
	ds_read_b128 v[198:201], v219 offset:5120
	ds_read_b128 v[202:205], v219 offset:6144
	ds_read_b128 v[206:209], v219 offset:7168
	global_load_lds_dwordx4 v[176:177], off
	v_lshl_add_u64 v[176:177], s[42:43], 0, v[192:193]
	s_add_i32 m0, s16, 0xe000
	s_nop 0
	global_load_lds_dwordx4 v[176:177], off
	s_add_i32 s1, 0, 0x14000
	v_add_u32_e32 v168, s1, v217
	ds_read_b128 v[230:233], v168
	ds_read_b128 v[234:237], v168 offset:1024
	ds_read_b128 v[238:241], v168 offset:2048
	ds_read_b128 v[242:245], v168 offset:3072
	s_waitcnt vmcnt(8)
	s_waitcnt lgkmcnt(0)
	s_barrier
	s_setprio 1
	v_mfma_f32_16x16x32_bf16 v[126:129], v[130:133], v[146:149], 0
	v_mfma_f32_16x16x32_bf16 v[122:125], v[138:141], v[146:149], 0
	v_mfma_f32_16x16x32_bf16 v[118:121], v[130:133], v[154:157], 0
	v_mfma_f32_16x16x32_bf16 v[110:113], v[138:141], v[154:157], 0
	v_mfma_f32_16x16x32_bf16 v[102:105], v[130:133], v[194:197], 0
	v_mfma_f32_16x16x32_bf16 v[94:97], v[138:141], v[194:197], 0
	v_mfma_f32_16x16x32_bf16 v[86:89], v[130:133], v[202:205], 0
	v_mfma_f32_16x16x32_bf16 v[78:81], v[138:141], v[202:205], 0
	v_mfma_f32_16x16x32_bf16 v[126:129], v[134:137], v[150:153], v[126:129]
	v_mfma_f32_16x16x32_bf16 v[122:125], v[142:145], v[150:153], v[122:125]
	v_mfma_f32_16x16x32_bf16 v[118:121], v[134:137], v[158:161], v[118:121]
	v_mfma_f32_16x16x32_bf16 v[110:113], v[142:145], v[158:161], v[110:113]
	v_mfma_f32_16x16x32_bf16 v[102:105], v[134:137], v[198:201], v[102:105]
	v_mfma_f32_16x16x32_bf16 v[94:97], v[142:145], v[198:201], v[94:97]
	v_mfma_f32_16x16x32_bf16 v[86:89], v[134:137], v[206:209], v[86:89]
	v_mfma_f32_16x16x32_bf16 v[78:81], v[142:145], v[206:209], v[78:81]
	v_mfma_f32_16x16x32_bf16 v[114:117], v[230:233], v[146:149], 0
	v_mfma_f32_16x16x32_bf16 v[106:109], v[238:241], v[146:149], 0
	v_mfma_f32_16x16x32_bf16 v[98:101], v[230:233], v[154:157], 0
	v_mfma_f32_16x16x32_bf16 v[90:93], v[238:241], v[154:157], 0
	v_mfma_f32_16x16x32_bf16 v[82:85], v[230:233], v[194:197], 0
	v_mfma_f32_16x16x32_bf16 v[74:77], v[238:241], v[194:197], 0
	v_mfma_f32_16x16x32_bf16 v[70:73], v[230:233], v[202:205], 0
	v_mfma_f32_16x16x32_bf16 v[66:69], v[238:241], v[202:205], 0
	v_mfma_f32_16x16x32_bf16 v[114:117], v[234:237], v[150:153], v[114:117]
	v_mfma_f32_16x16x32_bf16 v[106:109], v[242:245], v[150:153], v[106:109]
	v_mfma_f32_16x16x32_bf16 v[98:101], v[234:237], v[158:161], v[98:101]
	v_mfma_f32_16x16x32_bf16 v[90:93], v[242:245], v[158:161], v[90:93]
	v_mfma_f32_16x16x32_bf16 v[82:85], v[234:237], v[198:201], v[82:85]
	v_mfma_f32_16x16x32_bf16 v[74:77], v[242:245], v[198:201], v[74:77]
	v_mfma_f32_16x16x32_bf16 v[70:73], v[234:237], v[206:209], v[70:73]
	v_mfma_f32_16x16x32_bf16 v[66:69], v[242:245], v[206:209], v[66:69]
	s_setprio 0
	s_barrier
	ds_read_b128 v[146:149], v219 offset:16384
	ds_read_b128 v[150:153], v219 offset:17408
	ds_read_b128 v[154:157], v219 offset:18432
	ds_read_b128 v[158:161], v219 offset:19456
	ds_read_b128 v[194:197], v219 offset:20480
	ds_read_b128 v[198:201], v219 offset:21504
	ds_read_b128 v[202:205], v219 offset:22528
	ds_read_b128 v[206:209], v219 offset:23552
	s_add_i32 s22, s23, s4
	v_lshl_add_u64 v[176:177], s[30:31], 0, v[0:1]
	s_mov_b32 m0, s22
	s_nop 0
	global_load_lds_dwordx4 v[176:177], off
	v_lshl_add_u64 v[220:221], s[30:31], 0, v[178:179]
	s_add_i32 m0, s22, 0x2000
	s_nop 0
	global_load_lds_dwordx4 v[220:221], off
	s_mov_b32 m0, s16
	v_lshl_add_u64 v[246:247], s[44:45], 0, v[182:183]
	global_load_lds_dwordx4 v[246:247], off
	v_lshl_add_u64 v[248:249], s[44:45], 0, v[180:181]
	s_mov_b32 m0, s17
	s_nop 0
	global_load_lds_dwordx4 v[248:249], off
	s_add_u32 s22, s30, 0x40000
	s_addc_u32 s23, s31, 0
	s_add_i32 s1, s1, s4
	s_mov_b32 m0, s1
	s_nop 0
	global_load_lds_dwordx4 v0, s[22:23]
	s_add_i32 m0, s1, 0x2000
	s_nop 0
	global_load_lds_dwordx4 v178, s[22:23]
	s_waitcnt vmcnt(8)
	s_waitcnt lgkmcnt(0)
	s_barrier
	s_setprio 1
	v_mfma_f32_16x16x32_bf16 v[62:65], v[130:133], v[146:149], 0
	v_mfma_f32_16x16x32_bf16 v[58:61], v[138:141], v[146:149], 0
	v_mfma_f32_16x16x32_bf16 v[54:57], v[130:133], v[154:157], 0
	v_mfma_f32_16x16x32_bf16 v[46:49], v[138:141], v[154:157], 0
	v_mfma_f32_16x16x32_bf16 v[38:41], v[130:133], v[194:197], 0
	v_mfma_f32_16x16x32_bf16 v[30:33], v[138:141], v[194:197], 0
	v_mfma_f32_16x16x32_bf16 v[22:25], v[130:133], v[202:205], 0
	v_mfma_f32_16x16x32_bf16 v[14:17], v[138:141], v[202:205], 0
	v_mfma_f32_16x16x32_bf16 v[62:65], v[134:137], v[150:153], v[62:65]
	v_mfma_f32_16x16x32_bf16 v[58:61], v[142:145], v[150:153], v[58:61]
	v_mfma_f32_16x16x32_bf16 v[54:57], v[134:137], v[158:161], v[54:57]
	v_mfma_f32_16x16x32_bf16 v[46:49], v[142:145], v[158:161], v[46:49]
	v_mfma_f32_16x16x32_bf16 v[38:41], v[134:137], v[198:201], v[38:41]
	v_mfma_f32_16x16x32_bf16 v[30:33], v[142:145], v[198:201], v[30:33]
	v_mfma_f32_16x16x32_bf16 v[22:25], v[134:137], v[206:209], v[22:25]
	v_mfma_f32_16x16x32_bf16 v[14:17], v[142:145], v[206:209], v[14:17]
	v_mfma_f32_16x16x32_bf16 v[50:53], v[230:233], v[146:149], 0
	v_mfma_f32_16x16x32_bf16 v[42:45], v[238:241], v[146:149], 0
	v_mfma_f32_16x16x32_bf16 v[34:37], v[230:233], v[154:157], 0
	v_mfma_f32_16x16x32_bf16 v[26:29], v[238:241], v[154:157], 0
	v_mfma_f32_16x16x32_bf16 v[18:21], v[230:233], v[194:197], 0
	v_mfma_f32_16x16x32_bf16 v[10:13], v[238:241], v[194:197], 0
	v_mfma_f32_16x16x32_bf16 v[6:9], v[230:233], v[202:205], 0
	v_mfma_f32_16x16x32_bf16 v[2:5], v[238:241], v[202:205], 0
	v_mfma_f32_16x16x32_bf16 v[50:53], v[234:237], v[150:153], v[50:53]
	v_mfma_f32_16x16x32_bf16 v[42:45], v[242:245], v[150:153], v[42:45]
	v_mfma_f32_16x16x32_bf16 v[34:37], v[234:237], v[158:161], v[34:37]
	v_mfma_f32_16x16x32_bf16 v[26:29], v[242:245], v[158:161], v[26:29]
	v_mfma_f32_16x16x32_bf16 v[18:21], v[234:237], v[198:201], v[18:21]
	v_mfma_f32_16x16x32_bf16 v[10:13], v[242:245], v[198:201], v[10:13]
	v_mfma_f32_16x16x32_bf16 v[6:9], v[234:237], v[206:209], v[6:9]
	v_mfma_f32_16x16x32_bf16 v[2:5], v[242:245], v[206:209], v[2:5]
	s_setprio 0
	s_barrier
	s_add_i32 s1, 0, 0x18000
	v_add_u32_e32 v142, s1, v217
	ds_read_b128 v[130:133], v142
	ds_read_b128 v[134:137], v142 offset:1024
	ds_read_b128 v[138:141], v142 offset:2048
	ds_read_b128 v[142:145], v142 offset:3072
	s_add_u32 s22, s44, 0x40000
	s_addc_u32 s23, s45, 0
	s_mov_b32 m0, s20
	v_lshl_add_u64 v[230:231], s[22:23], 0, v[182:183]
	ds_read_b128 v[146:149], v219 offset:32768
	ds_read_b128 v[150:153], v219 offset:33792
	ds_read_b128 v[154:157], v219 offset:34816
	ds_read_b128 v[158:161], v219 offset:35840
	ds_read_b128 v[194:197], v219 offset:36864
	ds_read_b128 v[198:201], v219 offset:37888
	ds_read_b128 v[202:205], v219 offset:38912
	ds_read_b128 v[206:209], v219 offset:39936
	global_load_lds_dwordx4 v[230:231], off
	v_lshl_add_u64 v[230:231], s[22:23], 0, v[180:181]
	s_mov_b32 m0, s21
	s_nop 0
	global_load_lds_dwordx4 v[230:231], off
	s_add_i32 s33, 0, 0x1c000
	v_add_u32_e32 v168, s33, v217
	ds_read_b128 v[230:233], v168
	ds_read_b128 v[234:237], v168 offset:1024
	ds_read_b128 v[238:241], v168 offset:2048
	ds_read_b128 v[242:245], v168 offset:3072
	s_waitcnt vmcnt(8)
	s_waitcnt lgkmcnt(0)
	s_barrier
	s_setprio 1
	v_mfma_f32_16x16x32_bf16 v[126:129], v[130:133], v[146:149], v[126:129]
	v_mfma_f32_16x16x32_bf16 v[122:125], v[138:141], v[146:149], v[122:125]
	v_mfma_f32_16x16x32_bf16 v[118:121], v[130:133], v[154:157], v[118:121]
	v_mfma_f32_16x16x32_bf16 v[110:113], v[138:141], v[154:157], v[110:113]
	v_mfma_f32_16x16x32_bf16 v[102:105], v[130:133], v[194:197], v[102:105]
	v_mfma_f32_16x16x32_bf16 v[94:97], v[138:141], v[194:197], v[94:97]
	v_mfma_f32_16x16x32_bf16 v[86:89], v[130:133], v[202:205], v[86:89]
	v_mfma_f32_16x16x32_bf16 v[78:81], v[138:141], v[202:205], v[78:81]
	v_mfma_f32_16x16x32_bf16 v[126:129], v[134:137], v[150:153], v[126:129]
	v_mfma_f32_16x16x32_bf16 v[122:125], v[142:145], v[150:153], v[122:125]
	v_mfma_f32_16x16x32_bf16 v[118:121], v[134:137], v[158:161], v[118:121]
	v_mfma_f32_16x16x32_bf16 v[110:113], v[142:145], v[158:161], v[110:113]
	v_mfma_f32_16x16x32_bf16 v[102:105], v[134:137], v[198:201], v[102:105]
	v_mfma_f32_16x16x32_bf16 v[94:97], v[142:145], v[198:201], v[94:97]
	v_mfma_f32_16x16x32_bf16 v[86:89], v[134:137], v[206:209], v[86:89]
	v_mfma_f32_16x16x32_bf16 v[78:81], v[142:145], v[206:209], v[78:81]
	v_mfma_f32_16x16x32_bf16 v[114:117], v[230:233], v[146:149], v[114:117]
	v_mfma_f32_16x16x32_bf16 v[106:109], v[238:241], v[146:149], v[106:109]
	v_mfma_f32_16x16x32_bf16 v[98:101], v[230:233], v[154:157], v[98:101]
	v_mfma_f32_16x16x32_bf16 v[90:93], v[238:241], v[154:157], v[90:93]
	v_mfma_f32_16x16x32_bf16 v[82:85], v[230:233], v[194:197], v[82:85]
	v_mfma_f32_16x16x32_bf16 v[74:77], v[238:241], v[194:197], v[74:77]
	v_mfma_f32_16x16x32_bf16 v[70:73], v[230:233], v[202:205], v[70:73]
	v_mfma_f32_16x16x32_bf16 v[66:69], v[238:241], v[202:205], v[66:69]
	v_mfma_f32_16x16x32_bf16 v[114:117], v[234:237], v[150:153], v[114:117]
	v_mfma_f32_16x16x32_bf16 v[106:109], v[242:245], v[150:153], v[106:109]
	v_mfma_f32_16x16x32_bf16 v[98:101], v[234:237], v[158:161], v[98:101]
	v_mfma_f32_16x16x32_bf16 v[90:93], v[242:245], v[158:161], v[90:93]
	v_mfma_f32_16x16x32_bf16 v[82:85], v[234:237], v[198:201], v[82:85]
	v_mfma_f32_16x16x32_bf16 v[74:77], v[242:245], v[198:201], v[74:77]
	v_mfma_f32_16x16x32_bf16 v[70:73], v[234:237], v[206:209], v[70:73]
	v_mfma_f32_16x16x32_bf16 v[66:69], v[242:245], v[206:209], v[66:69]
	s_setprio 0
	s_barrier
	ds_read_b128 v[146:149], v219 offset:49152
	ds_read_b128 v[150:153], v219 offset:50176
	ds_read_b128 v[154:157], v219 offset:51200
	ds_read_b128 v[158:161], v219 offset:52224
	ds_read_b128 v[194:197], v219 offset:53248
	ds_read_b128 v[198:201], v219 offset:54272
	ds_read_b128 v[202:205], v219 offset:55296
	ds_read_b128 v[206:209], v219 offset:56320
	s_add_i32 s1, s1, s4
	v_lshl_add_u64 v[176:177], v[176:177], 0, s[12:13]
	s_mov_b32 m0, s1
	s_nop 0
	global_load_lds_dwordx4 v[176:177], off
	v_lshl_add_u64 v[176:177], v[220:221], 0, s[12:13]
	s_add_i32 m0, s1, 0x2000
	s_nop 0
	global_load_lds_dwordx4 v[176:177], off
	s_mov_b32 m0, s34
	v_lshl_add_u64 v[176:177], v[246:247], 0, s[12:13]
	global_load_lds_dwordx4 v[176:177], off
	v_lshl_add_u64 v[176:177], v[248:249], 0, s[12:13]
	s_mov_b32 m0, s46
	s_nop 0
	global_load_lds_dwordx4 v[176:177], off
	s_add_u32 s22, s30, 0x40080
	s_addc_u32 s23, s31, 0
	s_add_i32 s1, s33, s4
	s_mov_b32 m0, s1
	s_nop 0
	global_load_lds_dwordx4 v0, s[22:23]
	s_add_i32 m0, s1, 0x2000
	s_nop 0
	global_load_lds_dwordx4 v178, s[22:23]
	s_waitcnt vmcnt(8)
	s_waitcnt lgkmcnt(0)
	s_barrier
	s_setprio 1
	v_mfma_f32_16x16x32_bf16 v[62:65], v[130:133], v[146:149], v[62:65]
	v_mfma_f32_16x16x32_bf16 v[58:61], v[138:141], v[146:149], v[58:61]
	v_mfma_f32_16x16x32_bf16 v[54:57], v[130:133], v[154:157], v[54:57]
	v_mfma_f32_16x16x32_bf16 v[46:49], v[138:141], v[154:157], v[46:49]
	v_mfma_f32_16x16x32_bf16 v[38:41], v[130:133], v[194:197], v[38:41]
	v_mfma_f32_16x16x32_bf16 v[30:33], v[138:141], v[194:197], v[30:33]
	v_mfma_f32_16x16x32_bf16 v[22:25], v[130:133], v[202:205], v[22:25]
	v_mfma_f32_16x16x32_bf16 v[14:17], v[138:141], v[202:205], v[14:17]
	v_mfma_f32_16x16x32_bf16 v[62:65], v[134:137], v[150:153], v[62:65]
	v_mfma_f32_16x16x32_bf16 v[58:61], v[142:145], v[150:153], v[58:61]
	v_mfma_f32_16x16x32_bf16 v[54:57], v[134:137], v[158:161], v[54:57]
	v_mfma_f32_16x16x32_bf16 v[46:49], v[142:145], v[158:161], v[46:49]
	v_mfma_f32_16x16x32_bf16 v[38:41], v[134:137], v[198:201], v[38:41]
	v_mfma_f32_16x16x32_bf16 v[30:33], v[142:145], v[198:201], v[30:33]
	v_mfma_f32_16x16x32_bf16 v[22:25], v[134:137], v[206:209], v[22:25]
	v_mfma_f32_16x16x32_bf16 v[14:17], v[142:145], v[206:209], v[14:17]
	v_mfma_f32_16x16x32_bf16 v[50:53], v[230:233], v[146:149], v[50:53]
	v_mfma_f32_16x16x32_bf16 v[42:45], v[238:241], v[146:149], v[42:45]
	v_mfma_f32_16x16x32_bf16 v[34:37], v[230:233], v[154:157], v[34:37]
	v_mfma_f32_16x16x32_bf16 v[26:29], v[238:241], v[154:157], v[26:29]
	v_mfma_f32_16x16x32_bf16 v[18:21], v[230:233], v[194:197], v[18:21]
	v_mfma_f32_16x16x32_bf16 v[10:13], v[238:241], v[194:197], v[10:13]
	v_mfma_f32_16x16x32_bf16 v[6:9], v[230:233], v[202:205], v[6:9]
	v_mfma_f32_16x16x32_bf16 v[2:5], v[238:241], v[202:205], v[2:5]
	v_mfma_f32_16x16x32_bf16 v[50:53], v[234:237], v[150:153], v[50:53]
	v_mfma_f32_16x16x32_bf16 v[42:45], v[242:245], v[150:153], v[42:45]
	v_mfma_f32_16x16x32_bf16 v[34:37], v[234:237], v[158:161], v[34:37]
	v_mfma_f32_16x16x32_bf16 v[26:29], v[242:245], v[158:161], v[26:29]
	v_mfma_f32_16x16x32_bf16 v[18:21], v[234:237], v[198:201], v[18:21]
	v_mfma_f32_16x16x32_bf16 v[10:13], v[242:245], v[198:201], v[10:13]
	v_mfma_f32_16x16x32_bf16 v[6:9], v[234:237], v[206:209], v[6:9]
	v_mfma_f32_16x16x32_bf16 v[2:5], v[242:245], v[206:209], v[2:5]
	s_setprio 0
	s_add_i32 s54, s54, 2
	s_add_u32 s42, s42, 0x100
	s_addc_u32 s43, s43, 0
	s_add_u32 s52, s52, 0x100
	s_addc_u32 s53, s53, 0
	s_cmp_gt_u32 s54, 13
	s_barrier
.LBB0_289:
	s_add_u32 s1, s42, 0xfffc0080
	s_addc_u32 s22, s43, -1
	s_add_i32 s23, 0, 0x10000
	v_add_u32_e32 v142, s23, v217
	ds_read_b128 v[130:133], v142
	ds_read_b128 v[134:137], v142 offset:1024
	ds_read_b128 v[138:141], v142 offset:2048
	ds_read_b128 v[142:145], v142 offset:3072
	s_cmp_eq_u32 s54, 12
	s_cselect_b32 s45, s27, s22
	s_cselect_b32 s44, s50, s1
	s_cselect_b32 s31, s7, s53
	s_cselect_b32 s30, s51, s52
	v_lshl_add_u64 v[176:177], s[42:43], 0, v[190:191]
	s_add_i32 m0, s16, 0xc000
	ds_read_b128 v[146:149], v219
	ds_read_b128 v[150:153], v219 offset:1024
	ds_read_b128 v[154:157], v219 offset:2048
	ds_read_b128 v[158:161], v219 offset:3072
	ds_read_b128 v[194:197], v219 offset:4096
	ds_read_b128 v[198:201], v219 offset:5120
	ds_read_b128 v[202:205], v219 offset:6144
	ds_read_b128 v[206:209], v219 offset:7168
	global_load_lds_dwordx4 v[176:177], off
	v_lshl_add_u64 v[176:177], s[42:43], 0, v[192:193]
	s_add_i32 m0, s16, 0xe000
	s_nop 0
	global_load_lds_dwordx4 v[176:177], off
	s_add_i32 s1, 0, 0x14000
	v_add_u32_e32 v168, s1, v217
	ds_read_b128 v[230:233], v168
	ds_read_b128 v[234:237], v168 offset:1024
	ds_read_b128 v[238:241], v168 offset:2048
	ds_read_b128 v[242:245], v168 offset:3072
	s_waitcnt vmcnt(8)
	s_waitcnt lgkmcnt(0)
	s_barrier
	s_setprio 1
	v_mfma_f32_16x16x32_bf16 v[126:129], v[130:133], v[146:149], v[126:129]
	v_mfma_f32_16x16x32_bf16 v[122:125], v[138:141], v[146:149], v[122:125]
	v_mfma_f32_16x16x32_bf16 v[118:121], v[130:133], v[154:157], v[118:121]
	v_mfma_f32_16x16x32_bf16 v[110:113], v[138:141], v[154:157], v[110:113]
	v_mfma_f32_16x16x32_bf16 v[102:105], v[130:133], v[194:197], v[102:105]
	v_mfma_f32_16x16x32_bf16 v[94:97], v[138:141], v[194:197], v[94:97]
	v_mfma_f32_16x16x32_bf16 v[86:89], v[130:133], v[202:205], v[86:89]
	v_mfma_f32_16x16x32_bf16 v[78:81], v[138:141], v[202:205], v[78:81]
	v_mfma_f32_16x16x32_bf16 v[126:129], v[134:137], v[150:153], v[126:129]
	v_mfma_f32_16x16x32_bf16 v[122:125], v[142:145], v[150:153], v[122:125]
	v_mfma_f32_16x16x32_bf16 v[118:121], v[134:137], v[158:161], v[118:121]
	v_mfma_f32_16x16x32_bf16 v[110:113], v[142:145], v[158:161], v[110:113]
	v_mfma_f32_16x16x32_bf16 v[102:105], v[134:137], v[198:201], v[102:105]
	v_mfma_f32_16x16x32_bf16 v[94:97], v[142:145], v[198:201], v[94:97]
	v_mfma_f32_16x16x32_bf16 v[86:89], v[134:137], v[206:209], v[86:89]
	v_mfma_f32_16x16x32_bf16 v[78:81], v[142:145], v[206:209], v[78:81]
	v_mfma_f32_16x16x32_bf16 v[114:117], v[230:233], v[146:149], v[114:117]
	v_mfma_f32_16x16x32_bf16 v[106:109], v[238:241], v[146:149], v[106:109]
	v_mfma_f32_16x16x32_bf16 v[98:101], v[230:233], v[154:157], v[98:101]
	v_mfma_f32_16x16x32_bf16 v[90:93], v[238:241], v[154:157], v[90:93]
	v_mfma_f32_16x16x32_bf16 v[82:85], v[230:233], v[194:197], v[82:85]
	v_mfma_f32_16x16x32_bf16 v[74:77], v[238:241], v[194:197], v[74:77]
	v_mfma_f32_16x16x32_bf16 v[70:73], v[230:233], v[202:205], v[70:73]
	v_mfma_f32_16x16x32_bf16 v[66:69], v[238:241], v[202:205], v[66:69]
	v_mfma_f32_16x16x32_bf16 v[114:117], v[234:237], v[150:153], v[114:117]
	v_mfma_f32_16x16x32_bf16 v[106:109], v[242:245], v[150:153], v[106:109]
	v_mfma_f32_16x16x32_bf16 v[98:101], v[234:237], v[158:161], v[98:101]
	v_mfma_f32_16x16x32_bf16 v[90:93], v[242:245], v[158:161], v[90:93]
	v_mfma_f32_16x16x32_bf16 v[82:85], v[234:237], v[198:201], v[82:85]
	v_mfma_f32_16x16x32_bf16 v[74:77], v[242:245], v[198:201], v[74:77]
	v_mfma_f32_16x16x32_bf16 v[70:73], v[234:237], v[206:209], v[70:73]
	v_mfma_f32_16x16x32_bf16 v[66:69], v[242:245], v[206:209], v[66:69]
	s_setprio 0
	s_barrier
	ds_read_b128 v[146:149], v219 offset:16384
	ds_read_b128 v[150:153], v219 offset:17408
	ds_read_b128 v[154:157], v219 offset:18432
	ds_read_b128 v[158:161], v219 offset:19456
	ds_read_b128 v[194:197], v219 offset:20480
	ds_read_b128 v[198:201], v219 offset:21504
	ds_read_b128 v[202:205], v219 offset:22528
	ds_read_b128 v[206:209], v219 offset:23552
	s_add_i32 s22, s23, s4
	v_lshl_add_u64 v[176:177], s[30:31], 0, v[0:1]
	s_mov_b32 m0, s22
	s_nop 0
	global_load_lds_dwordx4 v[176:177], off
	v_lshl_add_u64 v[220:221], s[30:31], 0, v[178:179]
	s_add_i32 m0, s22, 0x2000
	s_nop 0
	global_load_lds_dwordx4 v[220:221], off
	s_mov_b32 m0, s16
	v_lshl_add_u64 v[246:247], s[44:45], 0, v[182:183]
	global_load_lds_dwordx4 v[246:247], off
	v_lshl_add_u64 v[248:249], s[44:45], 0, v[180:181]
	s_mov_b32 m0, s17
	s_nop 0
	global_load_lds_dwordx4 v[248:249], off
	s_add_u32 s22, s30, 0x40000
	s_addc_u32 s23, s31, 0
	s_add_i32 s1, s1, s4
	s_mov_b32 m0, s1
	s_nop 0
	global_load_lds_dwordx4 v0, s[22:23]
	s_add_i32 m0, s1, 0x2000
	s_nop 0
	global_load_lds_dwordx4 v178, s[22:23]
	s_waitcnt vmcnt(8)
	s_waitcnt lgkmcnt(0)
	s_barrier
	s_setprio 1
	v_mfma_f32_16x16x32_bf16 v[62:65], v[130:133], v[146:149], v[62:65]
	v_mfma_f32_16x16x32_bf16 v[58:61], v[138:141], v[146:149], v[58:61]
	v_mfma_f32_16x16x32_bf16 v[54:57], v[130:133], v[154:157], v[54:57]
	v_mfma_f32_16x16x32_bf16 v[46:49], v[138:141], v[154:157], v[46:49]
	v_mfma_f32_16x16x32_bf16 v[38:41], v[130:133], v[194:197], v[38:41]
	v_mfma_f32_16x16x32_bf16 v[30:33], v[138:141], v[194:197], v[30:33]
	v_mfma_f32_16x16x32_bf16 v[22:25], v[130:133], v[202:205], v[22:25]
	v_mfma_f32_16x16x32_bf16 v[14:17], v[138:141], v[202:205], v[14:17]
	v_mfma_f32_16x16x32_bf16 v[62:65], v[134:137], v[150:153], v[62:65]
	v_mfma_f32_16x16x32_bf16 v[58:61], v[142:145], v[150:153], v[58:61]
	v_mfma_f32_16x16x32_bf16 v[54:57], v[134:137], v[158:161], v[54:57]
	v_mfma_f32_16x16x32_bf16 v[46:49], v[142:145], v[158:161], v[46:49]
	v_mfma_f32_16x16x32_bf16 v[38:41], v[134:137], v[198:201], v[38:41]
	v_mfma_f32_16x16x32_bf16 v[30:33], v[142:145], v[198:201], v[30:33]
	v_mfma_f32_16x16x32_bf16 v[22:25], v[134:137], v[206:209], v[22:25]
	v_mfma_f32_16x16x32_bf16 v[14:17], v[142:145], v[206:209], v[14:17]
	v_mfma_f32_16x16x32_bf16 v[50:53], v[230:233], v[146:149], v[50:53]
	v_mfma_f32_16x16x32_bf16 v[42:45], v[238:241], v[146:149], v[42:45]
	v_mfma_f32_16x16x32_bf16 v[34:37], v[230:233], v[154:157], v[34:37]
	v_mfma_f32_16x16x32_bf16 v[26:29], v[238:241], v[154:157], v[26:29]
	v_mfma_f32_16x16x32_bf16 v[18:21], v[230:233], v[194:197], v[18:21]
	v_mfma_f32_16x16x32_bf16 v[10:13], v[238:241], v[194:197], v[10:13]
	v_mfma_f32_16x16x32_bf16 v[6:9], v[230:233], v[202:205], v[6:9]
	v_mfma_f32_16x16x32_bf16 v[2:5], v[238:241], v[202:205], v[2:5]
	v_mfma_f32_16x16x32_bf16 v[50:53], v[234:237], v[150:153], v[50:53]
	v_mfma_f32_16x16x32_bf16 v[42:45], v[242:245], v[150:153], v[42:45]
	v_mfma_f32_16x16x32_bf16 v[34:37], v[234:237], v[158:161], v[34:37]
	v_mfma_f32_16x16x32_bf16 v[26:29], v[242:245], v[158:161], v[26:29]
	v_mfma_f32_16x16x32_bf16 v[18:21], v[234:237], v[198:201], v[18:21]
	v_mfma_f32_16x16x32_bf16 v[10:13], v[242:245], v[198:201], v[10:13]
	v_mfma_f32_16x16x32_bf16 v[6:9], v[234:237], v[206:209], v[6:9]
	v_mfma_f32_16x16x32_bf16 v[2:5], v[242:245], v[206:209], v[2:5]
	s_setprio 0
	s_barrier
	s_add_i32 s1, 0, 0x18000
	v_add_u32_e32 v142, s1, v217
	ds_read_b128 v[130:133], v142
	ds_read_b128 v[134:137], v142 offset:1024
	ds_read_b128 v[138:141], v142 offset:2048
	ds_read_b128 v[142:145], v142 offset:3072
	s_add_u32 s22, s44, 0x40000
	s_addc_u32 s23, s45, 0
	s_mov_b32 m0, s20
	v_lshl_add_u64 v[230:231], s[22:23], 0, v[182:183]
	ds_read_b128 v[146:149], v219 offset:32768
	ds_read_b128 v[150:153], v219 offset:33792
	ds_read_b128 v[154:157], v219 offset:34816
	ds_read_b128 v[158:161], v219 offset:35840
	ds_read_b128 v[194:197], v219 offset:36864
	ds_read_b128 v[198:201], v219 offset:37888
	ds_read_b128 v[202:205], v219 offset:38912
	ds_read_b128 v[206:209], v219 offset:39936
	global_load_lds_dwordx4 v[230:231], off
	v_lshl_add_u64 v[230:231], s[22:23], 0, v[180:181]
	s_mov_b32 m0, s21
	s_nop 0
	global_load_lds_dwordx4 v[230:231], off
	s_add_i32 s33, 0, 0x1c000
	v_add_u32_e32 v168, s33, v217
	ds_read_b128 v[230:233], v168
	ds_read_b128 v[234:237], v168 offset:1024
	ds_read_b128 v[238:241], v168 offset:2048
	ds_read_b128 v[242:245], v168 offset:3072
	s_waitcnt vmcnt(8)
	s_waitcnt lgkmcnt(0)
	s_barrier
	s_setprio 1
	v_mfma_f32_16x16x32_bf16 v[126:129], v[130:133], v[146:149], v[126:129]
	v_mfma_f32_16x16x32_bf16 v[122:125], v[138:141], v[146:149], v[122:125]
	v_mfma_f32_16x16x32_bf16 v[118:121], v[130:133], v[154:157], v[118:121]
	v_mfma_f32_16x16x32_bf16 v[110:113], v[138:141], v[154:157], v[110:113]
	v_mfma_f32_16x16x32_bf16 v[102:105], v[130:133], v[194:197], v[102:105]
	v_mfma_f32_16x16x32_bf16 v[94:97], v[138:141], v[194:197], v[94:97]
	v_mfma_f32_16x16x32_bf16 v[86:89], v[130:133], v[202:205], v[86:89]
	v_mfma_f32_16x16x32_bf16 v[78:81], v[138:141], v[202:205], v[78:81]
	v_mfma_f32_16x16x32_bf16 v[126:129], v[134:137], v[150:153], v[126:129]
	v_mfma_f32_16x16x32_bf16 v[122:125], v[142:145], v[150:153], v[122:125]
	v_mfma_f32_16x16x32_bf16 v[118:121], v[134:137], v[158:161], v[118:121]
	v_mfma_f32_16x16x32_bf16 v[110:113], v[142:145], v[158:161], v[110:113]
	v_mfma_f32_16x16x32_bf16 v[102:105], v[134:137], v[198:201], v[102:105]
	v_mfma_f32_16x16x32_bf16 v[94:97], v[142:145], v[198:201], v[94:97]
	v_mfma_f32_16x16x32_bf16 v[86:89], v[134:137], v[206:209], v[86:89]
	v_mfma_f32_16x16x32_bf16 v[78:81], v[142:145], v[206:209], v[78:81]
	v_mfma_f32_16x16x32_bf16 v[114:117], v[230:233], v[146:149], v[114:117]
	v_mfma_f32_16x16x32_bf16 v[106:109], v[238:241], v[146:149], v[106:109]
	v_mfma_f32_16x16x32_bf16 v[98:101], v[230:233], v[154:157], v[98:101]
	v_mfma_f32_16x16x32_bf16 v[90:93], v[238:241], v[154:157], v[90:93]
	v_mfma_f32_16x16x32_bf16 v[82:85], v[230:233], v[194:197], v[82:85]
	v_mfma_f32_16x16x32_bf16 v[74:77], v[238:241], v[194:197], v[74:77]
	v_mfma_f32_16x16x32_bf16 v[70:73], v[230:233], v[202:205], v[70:73]
	v_mfma_f32_16x16x32_bf16 v[66:69], v[238:241], v[202:205], v[66:69]
	v_mfma_f32_16x16x32_bf16 v[114:117], v[234:237], v[150:153], v[114:117]
	v_mfma_f32_16x16x32_bf16 v[106:109], v[242:245], v[150:153], v[106:109]
	v_mfma_f32_16x16x32_bf16 v[98:101], v[234:237], v[158:161], v[98:101]
	v_mfma_f32_16x16x32_bf16 v[90:93], v[242:245], v[158:161], v[90:93]
	v_mfma_f32_16x16x32_bf16 v[82:85], v[234:237], v[198:201], v[82:85]
	v_mfma_f32_16x16x32_bf16 v[74:77], v[242:245], v[198:201], v[74:77]
	v_mfma_f32_16x16x32_bf16 v[70:73], v[234:237], v[206:209], v[70:73]
	v_mfma_f32_16x16x32_bf16 v[66:69], v[242:245], v[206:209], v[66:69]
	s_setprio 0
	s_barrier
	ds_read_b128 v[146:149], v219 offset:49152
	ds_read_b128 v[150:153], v219 offset:50176
	ds_read_b128 v[154:157], v219 offset:51200
	ds_read_b128 v[158:161], v219 offset:52224
	ds_read_b128 v[194:197], v219 offset:53248
	ds_read_b128 v[198:201], v219 offset:54272
	ds_read_b128 v[202:205], v219 offset:55296
	ds_read_b128 v[206:209], v219 offset:56320
	s_add_i32 s1, s1, s4
	v_lshl_add_u64 v[176:177], v[176:177], 0, s[12:13]
	s_mov_b32 m0, s1
	s_nop 0
	global_load_lds_dwordx4 v[176:177], off
	v_lshl_add_u64 v[176:177], v[220:221], 0, s[12:13]
	s_add_i32 m0, s1, 0x2000
	s_nop 0
	global_load_lds_dwordx4 v[176:177], off
	s_mov_b32 m0, s34
	v_lshl_add_u64 v[176:177], v[246:247], 0, s[12:13]
	global_load_lds_dwordx4 v[176:177], off
	v_lshl_add_u64 v[176:177], v[248:249], 0, s[12:13]
	s_mov_b32 m0, s46
	s_nop 0
	global_load_lds_dwordx4 v[176:177], off
	s_add_u32 s22, s30, 0x40080
	s_addc_u32 s23, s31, 0
	s_add_i32 s1, s33, s4
	s_mov_b32 m0, s1
	s_nop 0
	global_load_lds_dwordx4 v0, s[22:23]
	s_add_i32 m0, s1, 0x2000
	s_nop 0
	global_load_lds_dwordx4 v178, s[22:23]
	s_waitcnt vmcnt(8)
	s_waitcnt lgkmcnt(0)
	s_barrier
	s_setprio 1
	v_mfma_f32_16x16x32_bf16 v[62:65], v[130:133], v[146:149], v[62:65]
	v_mfma_f32_16x16x32_bf16 v[58:61], v[138:141], v[146:149], v[58:61]
	v_mfma_f32_16x16x32_bf16 v[54:57], v[130:133], v[154:157], v[54:57]
	v_mfma_f32_16x16x32_bf16 v[46:49], v[138:141], v[154:157], v[46:49]
	v_mfma_f32_16x16x32_bf16 v[38:41], v[130:133], v[194:197], v[38:41]
	v_mfma_f32_16x16x32_bf16 v[30:33], v[138:141], v[194:197], v[30:33]
	v_mfma_f32_16x16x32_bf16 v[22:25], v[130:133], v[202:205], v[22:25]
	v_mfma_f32_16x16x32_bf16 v[14:17], v[138:141], v[202:205], v[14:17]
	v_mfma_f32_16x16x32_bf16 v[62:65], v[134:137], v[150:153], v[62:65]
	v_mfma_f32_16x16x32_bf16 v[58:61], v[142:145], v[150:153], v[58:61]
	v_mfma_f32_16x16x32_bf16 v[54:57], v[134:137], v[158:161], v[54:57]
	v_mfma_f32_16x16x32_bf16 v[46:49], v[142:145], v[158:161], v[46:49]
	v_mfma_f32_16x16x32_bf16 v[38:41], v[134:137], v[198:201], v[38:41]
	v_mfma_f32_16x16x32_bf16 v[30:33], v[142:145], v[198:201], v[30:33]
	v_mfma_f32_16x16x32_bf16 v[22:25], v[134:137], v[206:209], v[22:25]
	v_mfma_f32_16x16x32_bf16 v[14:17], v[142:145], v[206:209], v[14:17]
	v_mfma_f32_16x16x32_bf16 v[50:53], v[230:233], v[146:149], v[50:53]
	v_mfma_f32_16x16x32_bf16 v[42:45], v[238:241], v[146:149], v[42:45]
	v_mfma_f32_16x16x32_bf16 v[34:37], v[230:233], v[154:157], v[34:37]
	v_mfma_f32_16x16x32_bf16 v[26:29], v[238:241], v[154:157], v[26:29]
	v_mfma_f32_16x16x32_bf16 v[18:21], v[230:233], v[194:197], v[18:21]
	v_mfma_f32_16x16x32_bf16 v[10:13], v[238:241], v[194:197], v[10:13]
	v_mfma_f32_16x16x32_bf16 v[6:9], v[230:233], v[202:205], v[6:9]
	v_mfma_f32_16x16x32_bf16 v[2:5], v[238:241], v[202:205], v[2:5]
	v_mfma_f32_16x16x32_bf16 v[50:53], v[234:237], v[150:153], v[50:53]
	v_mfma_f32_16x16x32_bf16 v[42:45], v[242:245], v[150:153], v[42:45]
	v_mfma_f32_16x16x32_bf16 v[34:37], v[234:237], v[158:161], v[34:37]
	v_mfma_f32_16x16x32_bf16 v[26:29], v[242:245], v[158:161], v[26:29]
	v_mfma_f32_16x16x32_bf16 v[18:21], v[234:237], v[198:201], v[18:21]
	v_mfma_f32_16x16x32_bf16 v[10:13], v[242:245], v[198:201], v[10:13]
	v_mfma_f32_16x16x32_bf16 v[6:9], v[234:237], v[206:209], v[6:9]
	v_mfma_f32_16x16x32_bf16 v[2:5], v[242:245], v[206:209], v[2:5]
	s_setprio 0
	s_add_i32 s54, s54, 2
	s_add_u32 s42, s42, 0x100
	s_addc_u32 s43, s43, 0
	s_add_u32 s52, s52, 0x100
	s_addc_u32 s53, s53, 0
	s_cmp_gt_u32 s54, 13
	s_barrier
	s_cbranch_scc0 .LBB0_289
	s_cmpk_gt_u32 s0, 0xff
	s_cbranch_scc1 .Lrs_proj0_post
	s_barrier

.LBB0_361:
	s_ashr_i32 s25, s24, 31
	s_lshl_b64 s[20:21], s[24:25], 19
	v_cmp_lt_i64_e32 vcc, s[26:27], v[174:175]
	s_add_u32 s26, s46, s20
	s_addc_u32 s27, s47, s21
	s_and_b64 s[20:21], vcc, exec
	s_cselect_b32 s17, s27, s29
	s_cselect_b32 s20, s26, s28
	s_ashr_i32 s9, s8, 31
	s_lshl_b64 s[22:23], s[8:9], 19
	v_readlane_b32 s36, v254, 42
	v_readlane_b32 s37, v254, 43
	s_add_u32 s36, s36, s22
	s_addc_u32 s37, s37, s23
	s_and_b64 s[22:23], vcc, exec
	s_cselect_b32 s9, s37, s31
	s_cselect_b32 s21, s36, s30
	s_add_u32 s28, s28, 0x40080
	s_addc_u32 s29, s29, 0
	s_add_u32 s25, s30, 0x100
	s_addc_u32 s34, s31, 0
	s_mov_b32 s44, -2
	s_cmpk_gt_u32 s4, 0xff
	s_cbranch_scc0 .Lrs_proj1_pre
	s_barrier
.Lrs_proj1_pre:
	s_add_u32 s1, s28, 0xfffc0080
	s_addc_u32 s22, s29, -1
	s_add_i32 s23, 0, 0x10000
	v_add_u32_e32 v158, s23, v181
	ds_read_b128 v[130:133], v158
	ds_read_b128 v[134:137], v158 offset:1024
	ds_read_b128 v[154:157], v158 offset:2048
	ds_read_b128 v[186:189], v158 offset:3072
	s_cmp_eq_u32 s44, 12
	s_cselect_b32 s43, s17, s22
	s_cselect_b32 s42, s20, s1
	s_cselect_b32 s31, s9, s34
	s_cselect_b32 s30, s21, s25
	v_lshl_add_u64 v[160:161], s[28:29], 0, v[150:151]
	s_add_i32 m0, s49, 0xc000
	ds_read_b128 v[190:193], v185
	ds_read_b128 v[194:197], v185 offset:1024
	ds_read_b128 v[198:201], v185 offset:2048
	ds_read_b128 v[202:205], v185 offset:3072
	ds_read_b128 v[206:209], v185 offset:4096
	ds_read_b128 v[216:219], v185 offset:5120
	ds_read_b128 v[230:233], v185 offset:6144
	ds_read_b128 v[234:237], v185 offset:7168
	global_load_lds_dwordx4 v[160:161], off
	v_lshl_add_u64 v[160:161], s[28:29], 0, v[152:153]
	s_add_i32 m0, s49, 0xe000
	s_nop 0
	global_load_lds_dwordx4 v[160:161], off
	s_add_i32 s1, 0, 0x14000
	v_add_u32_e32 v158, s1, v181
	ds_read_b128 v[238:241], v158
	ds_read_b128 v[242:245], v158 offset:1024
	ds_read_b128 v[246:249], v158 offset:2048
	ds_read_b128 v[176:179], v158 offset:3072
	s_waitcnt vmcnt(8)
	s_waitcnt lgkmcnt(0)
	s_barrier
	s_setprio 1
	v_mfma_f32_16x16x32_bf16 v[126:129], v[130:133], v[190:193], 0
	v_mfma_f32_16x16x32_bf16 v[122:125], v[154:157], v[190:193], 0
	v_mfma_f32_16x16x32_bf16 v[110:113], v[130:133], v[198:201], 0
	v_mfma_f32_16x16x32_bf16 v[106:109], v[154:157], v[198:201], 0
	v_mfma_f32_16x16x32_bf16 v[94:97], v[130:133], v[206:209], 0
	v_mfma_f32_16x16x32_bf16 v[90:93], v[154:157], v[206:209], 0
	v_mfma_f32_16x16x32_bf16 v[78:81], v[130:133], v[230:233], 0
	v_mfma_f32_16x16x32_bf16 v[74:77], v[154:157], v[230:233], 0
	v_mfma_f32_16x16x32_bf16 v[126:129], v[134:137], v[194:197], v[126:129]
	v_mfma_f32_16x16x32_bf16 v[122:125], v[186:189], v[194:197], v[122:125]
	v_mfma_f32_16x16x32_bf16 v[110:113], v[134:137], v[202:205], v[110:113]
	v_mfma_f32_16x16x32_bf16 v[106:109], v[186:189], v[202:205], v[106:109]
	v_mfma_f32_16x16x32_bf16 v[94:97], v[134:137], v[216:219], v[94:97]
	v_mfma_f32_16x16x32_bf16 v[90:93], v[186:189], v[216:219], v[90:93]
	v_mfma_f32_16x16x32_bf16 v[78:81], v[134:137], v[234:237], v[78:81]
	v_mfma_f32_16x16x32_bf16 v[74:77], v[186:189], v[234:237], v[74:77]
	v_mfma_f32_16x16x32_bf16 v[118:121], v[238:241], v[190:193], 0
	v_mfma_f32_16x16x32_bf16 v[114:117], v[246:249], v[190:193], 0
	v_mfma_f32_16x16x32_bf16 v[102:105], v[238:241], v[198:201], 0
	v_mfma_f32_16x16x32_bf16 v[98:101], v[246:249], v[198:201], 0
	v_mfma_f32_16x16x32_bf16 v[86:89], v[238:241], v[206:209], 0
	v_mfma_f32_16x16x32_bf16 v[82:85], v[246:249], v[206:209], 0
	v_mfma_f32_16x16x32_bf16 v[70:73], v[238:241], v[230:233], 0
	v_mfma_f32_16x16x32_bf16 v[66:69], v[246:249], v[230:233], 0
	v_mfma_f32_16x16x32_bf16 v[118:121], v[242:245], v[194:197], v[118:121]
	v_mfma_f32_16x16x32_bf16 v[114:117], v[176:179], v[194:197], v[114:117]
	v_mfma_f32_16x16x32_bf16 v[102:105], v[242:245], v[202:205], v[102:105]
	v_mfma_f32_16x16x32_bf16 v[98:101], v[176:179], v[202:205], v[98:101]
	v_mfma_f32_16x16x32_bf16 v[86:89], v[242:245], v[216:219], v[86:89]
	v_mfma_f32_16x16x32_bf16 v[82:85], v[176:179], v[216:219], v[82:85]
	v_mfma_f32_16x16x32_bf16 v[70:73], v[242:245], v[234:237], v[70:73]
	v_mfma_f32_16x16x32_bf16 v[66:69], v[176:179], v[234:237], v[66:69]
	s_setprio 0
	s_barrier
	ds_read_b128 v[190:193], v185 offset:16384
	ds_read_b128 v[194:197], v185 offset:17408
	ds_read_b128 v[198:201], v185 offset:18432
	ds_read_b128 v[202:205], v185 offset:19456
	ds_read_b128 v[206:209], v185 offset:20480
	ds_read_b128 v[216:219], v185 offset:21504
	ds_read_b128 v[230:233], v185 offset:22528
	ds_read_b128 v[234:237], v185 offset:23552
	s_add_i32 s22, s23, s48
	v_lshl_add_u64 v[160:161], s[30:31], 0, v[0:1]
	s_mov_b32 m0, s22
	s_nop 0
	global_load_lds_dwordx4 v[160:161], off
	v_lshl_add_u64 v[220:221], s[30:31], 0, v[138:139]
	s_add_i32 m0, s22, 0x2000
	s_nop 0
	global_load_lds_dwordx4 v[220:221], off
	s_mov_b32 m0, s49
	v_lshl_add_u64 v[250:251], s[42:43], 0, v[142:143]
	global_load_lds_dwordx4 v[250:251], off
	v_lshl_add_u64 v[168:169], s[42:43], 0, v[140:141]
	s_mov_b32 m0, s50
	s_nop 0
	global_load_lds_dwordx4 v[168:169], off
	s_add_u32 s22, s30, 0x40000
	s_addc_u32 s23, s31, 0
	s_add_i32 s1, s1, s48
	s_mov_b32 m0, s1
	s_nop 0
	global_load_lds_dwordx4 v0, s[22:23]
	s_add_i32 m0, s1, 0x2000
	s_nop 0
	global_load_lds_dwordx4 v138, s[22:23]
	s_waitcnt vmcnt(8)
	s_waitcnt lgkmcnt(0)
	s_barrier
	s_setprio 1
	v_mfma_f32_16x16x32_bf16 v[62:65], v[130:133], v[190:193], 0
	v_mfma_f32_16x16x32_bf16 v[58:61], v[154:157], v[190:193], 0
	v_mfma_f32_16x16x32_bf16 v[46:49], v[130:133], v[198:201], 0
	v_mfma_f32_16x16x32_bf16 v[42:45], v[154:157], v[198:201], 0
	v_mfma_f32_16x16x32_bf16 v[30:33], v[130:133], v[206:209], 0
	v_mfma_f32_16x16x32_bf16 v[26:29], v[154:157], v[206:209], 0
	v_mfma_f32_16x16x32_bf16 v[14:17], v[130:133], v[230:233], 0
	v_mfma_f32_16x16x32_bf16 v[10:13], v[154:157], v[230:233], 0
	v_mfma_f32_16x16x32_bf16 v[62:65], v[134:137], v[194:197], v[62:65]
	v_mfma_f32_16x16x32_bf16 v[58:61], v[186:189], v[194:197], v[58:61]
	v_mfma_f32_16x16x32_bf16 v[46:49], v[134:137], v[202:205], v[46:49]
	v_mfma_f32_16x16x32_bf16 v[42:45], v[186:189], v[202:205], v[42:45]
	v_mfma_f32_16x16x32_bf16 v[30:33], v[134:137], v[216:219], v[30:33]
	v_mfma_f32_16x16x32_bf16 v[26:29], v[186:189], v[216:219], v[26:29]
	v_mfma_f32_16x16x32_bf16 v[14:17], v[134:137], v[234:237], v[14:17]
	v_mfma_f32_16x16x32_bf16 v[10:13], v[186:189], v[234:237], v[10:13]
	v_mfma_f32_16x16x32_bf16 v[54:57], v[238:241], v[190:193], 0
	v_mfma_f32_16x16x32_bf16 v[50:53], v[246:249], v[190:193], 0
	v_mfma_f32_16x16x32_bf16 v[38:41], v[238:241], v[198:201], 0
	v_mfma_f32_16x16x32_bf16 v[34:37], v[246:249], v[198:201], 0
	v_mfma_f32_16x16x32_bf16 v[22:25], v[238:241], v[206:209], 0
	v_mfma_f32_16x16x32_bf16 v[18:21], v[246:249], v[206:209], 0
	v_mfma_f32_16x16x32_bf16 v[6:9], v[238:241], v[230:233], 0
	v_mfma_f32_16x16x32_bf16 v[2:5], v[246:249], v[230:233], 0
	v_mfma_f32_16x16x32_bf16 v[54:57], v[242:245], v[194:197], v[54:57]
	v_mfma_f32_16x16x32_bf16 v[50:53], v[176:179], v[194:197], v[50:53]
	v_mfma_f32_16x16x32_bf16 v[38:41], v[242:245], v[202:205], v[38:41]
	v_mfma_f32_16x16x32_bf16 v[34:37], v[176:179], v[202:205], v[34:37]
	v_mfma_f32_16x16x32_bf16 v[22:25], v[242:245], v[216:219], v[22:25]
	v_mfma_f32_16x16x32_bf16 v[18:21], v[176:179], v[216:219], v[18:21]
	v_mfma_f32_16x16x32_bf16 v[6:9], v[242:245], v[234:237], v[6:9]
	v_mfma_f32_16x16x32_bf16 v[2:5], v[176:179], v[234:237], v[2:5]
	s_setprio 0
	s_barrier
	s_add_i32 s1, 0, 0x18000
	v_add_u32_e32 v158, s1, v181
	ds_read_b128 v[130:133], v158
	ds_read_b128 v[134:137], v158 offset:1024
	ds_read_b128 v[154:157], v158 offset:2048
	ds_read_b128 v[176:179], v158 offset:3072
	s_add_u32 s22, s42, 0x40000
	s_addc_u32 s23, s43, 0
	s_mov_b32 m0, s51
	v_lshl_add_u64 v[234:235], s[22:23], 0, v[142:143]
	ds_read_b128 v[186:189], v185 offset:32768
	ds_read_b128 v[190:193], v185 offset:33792
	ds_read_b128 v[194:197], v185 offset:34816
	ds_read_b128 v[198:201], v185 offset:35840
	ds_read_b128 v[202:205], v185 offset:36864
	ds_read_b128 v[206:209], v185 offset:37888
	ds_read_b128 v[216:219], v185 offset:38912
	ds_read_b128 v[230:233], v185 offset:39936
	global_load_lds_dwordx4 v[234:235], off
	v_lshl_add_u64 v[234:235], s[22:23], 0, v[140:141]
	s_mov_b32 m0, s52
	s_nop 0
	global_load_lds_dwordx4 v[234:235], off
	s_add_i32 s33, 0, 0x1c000
	v_add_u32_e32 v158, s33, v181
	ds_read_b128 v[234:237], v158
	ds_read_b128 v[238:241], v158 offset:1024
	ds_read_b128 v[242:245], v158 offset:2048
	ds_read_b128 v[246:249], v158 offset:3072
	s_waitcnt vmcnt(8)
	s_waitcnt lgkmcnt(0)
	s_barrier
	s_setprio 1
	v_mfma_f32_16x16x32_bf16 v[126:129], v[130:133], v[186:189], v[126:129]
	v_mfma_f32_16x16x32_bf16 v[122:125], v[154:157], v[186:189], v[122:125]
	v_mfma_f32_16x16x32_bf16 v[110:113], v[130:133], v[194:197], v[110:113]
	v_mfma_f32_16x16x32_bf16 v[106:109], v[154:157], v[194:197], v[106:109]
	v_mfma_f32_16x16x32_bf16 v[94:97], v[130:133], v[202:205], v[94:97]
	v_mfma_f32_16x16x32_bf16 v[90:93], v[154:157], v[202:205], v[90:93]
	v_mfma_f32_16x16x32_bf16 v[78:81], v[130:133], v[216:219], v[78:81]
	v_mfma_f32_16x16x32_bf16 v[74:77], v[154:157], v[216:219], v[74:77]
	v_mfma_f32_16x16x32_bf16 v[126:129], v[134:137], v[190:193], v[126:129]
	v_mfma_f32_16x16x32_bf16 v[122:125], v[176:179], v[190:193], v[122:125]
	v_mfma_f32_16x16x32_bf16 v[110:113], v[134:137], v[198:201], v[110:113]
	v_mfma_f32_16x16x32_bf16 v[106:109], v[176:179], v[198:201], v[106:109]
	v_mfma_f32_16x16x32_bf16 v[94:97], v[134:137], v[206:209], v[94:97]
	v_mfma_f32_16x16x32_bf16 v[90:93], v[176:179], v[206:209], v[90:93]
	v_mfma_f32_16x16x32_bf16 v[78:81], v[134:137], v[230:233], v[78:81]
	v_mfma_f32_16x16x32_bf16 v[74:77], v[176:179], v[230:233], v[74:77]
	v_mfma_f32_16x16x32_bf16 v[118:121], v[234:237], v[186:189], v[118:121]
	v_mfma_f32_16x16x32_bf16 v[114:117], v[242:245], v[186:189], v[114:117]
	v_mfma_f32_16x16x32_bf16 v[102:105], v[234:237], v[194:197], v[102:105]
	v_mfma_f32_16x16x32_bf16 v[98:101], v[242:245], v[194:197], v[98:101]
	v_mfma_f32_16x16x32_bf16 v[86:89], v[234:237], v[202:205], v[86:89]
	v_mfma_f32_16x16x32_bf16 v[82:85], v[242:245], v[202:205], v[82:85]
	v_mfma_f32_16x16x32_bf16 v[70:73], v[234:237], v[216:219], v[70:73]
	v_mfma_f32_16x16x32_bf16 v[66:69], v[242:245], v[216:219], v[66:69]
	v_mfma_f32_16x16x32_bf16 v[118:121], v[238:241], v[190:193], v[118:121]
	v_mfma_f32_16x16x32_bf16 v[114:117], v[246:249], v[190:193], v[114:117]
	v_mfma_f32_16x16x32_bf16 v[102:105], v[238:241], v[198:201], v[102:105]
	v_mfma_f32_16x16x32_bf16 v[98:101], v[246:249], v[198:201], v[98:101]
	v_mfma_f32_16x16x32_bf16 v[86:89], v[238:241], v[206:209], v[86:89]
	v_mfma_f32_16x16x32_bf16 v[82:85], v[246:249], v[206:209], v[82:85]
	v_mfma_f32_16x16x32_bf16 v[70:73], v[238:241], v[230:233], v[70:73]
	v_mfma_f32_16x16x32_bf16 v[66:69], v[246:249], v[230:233], v[66:69]
	s_setprio 0
	s_barrier
	ds_read_b128 v[186:189], v185 offset:49152
	ds_read_b128 v[190:193], v185 offset:50176
	ds_read_b128 v[194:197], v185 offset:51200
	ds_read_b128 v[198:201], v185 offset:52224
	ds_read_b128 v[202:205], v185 offset:53248
	ds_read_b128 v[206:209], v185 offset:54272
	ds_read_b128 v[216:219], v185 offset:55296
	ds_read_b128 v[230:233], v185 offset:56320
	s_add_i32 s1, s1, s48
	v_lshl_add_u64 v[160:161], v[160:161], 0, s[12:13]
	s_mov_b32 m0, s1
	s_nop 0
	global_load_lds_dwordx4 v[160:161], off
	v_lshl_add_u64 v[160:161], v[220:221], 0, s[12:13]
	s_add_i32 m0, s1, 0x2000
	s_nop 0
	global_load_lds_dwordx4 v[160:161], off
	s_mov_b32 m0, s55
	v_lshl_add_u64 v[160:161], v[250:251], 0, s[12:13]
	global_load_lds_dwordx4 v[160:161], off
	v_lshl_add_u64 v[160:161], v[168:169], 0, s[12:13]
	s_mov_b32 m0, s56
	s_nop 0
	global_load_lds_dwordx4 v[160:161], off
	s_add_u32 s22, s30, 0x40080
	s_addc_u32 s23, s31, 0
	s_add_i32 s1, s33, s48
	s_mov_b32 m0, s1
	s_nop 0
	global_load_lds_dwordx4 v0, s[22:23]
	s_add_i32 m0, s1, 0x2000
	s_nop 0
	global_load_lds_dwordx4 v138, s[22:23]
	s_waitcnt vmcnt(8)
	s_waitcnt lgkmcnt(0)
	s_barrier
	s_setprio 1
	v_mfma_f32_16x16x32_bf16 v[62:65], v[130:133], v[186:189], v[62:65]
	v_mfma_f32_16x16x32_bf16 v[58:61], v[154:157], v[186:189], v[58:61]
	v_mfma_f32_16x16x32_bf16 v[46:49], v[130:133], v[194:197], v[46:49]
	v_mfma_f32_16x16x32_bf16 v[42:45], v[154:157], v[194:197], v[42:45]
	v_mfma_f32_16x16x32_bf16 v[30:33], v[130:133], v[202:205], v[30:33]
	v_mfma_f32_16x16x32_bf16 v[26:29], v[154:157], v[202:205], v[26:29]
	v_mfma_f32_16x16x32_bf16 v[14:17], v[130:133], v[216:219], v[14:17]
	v_mfma_f32_16x16x32_bf16 v[10:13], v[154:157], v[216:219], v[10:13]
	v_mfma_f32_16x16x32_bf16 v[62:65], v[134:137], v[190:193], v[62:65]
	v_mfma_f32_16x16x32_bf16 v[58:61], v[176:179], v[190:193], v[58:61]
	v_mfma_f32_16x16x32_bf16 v[46:49], v[134:137], v[198:201], v[46:49]
	v_mfma_f32_16x16x32_bf16 v[42:45], v[176:179], v[198:201], v[42:45]
	v_mfma_f32_16x16x32_bf16 v[30:33], v[134:137], v[206:209], v[30:33]
	v_mfma_f32_16x16x32_bf16 v[26:29], v[176:179], v[206:209], v[26:29]
	v_mfma_f32_16x16x32_bf16 v[14:17], v[134:137], v[230:233], v[14:17]
	v_mfma_f32_16x16x32_bf16 v[10:13], v[176:179], v[230:233], v[10:13]
	v_mfma_f32_16x16x32_bf16 v[54:57], v[234:237], v[186:189], v[54:57]
	v_mfma_f32_16x16x32_bf16 v[50:53], v[242:245], v[186:189], v[50:53]
	v_mfma_f32_16x16x32_bf16 v[38:41], v[234:237], v[194:197], v[38:41]
	v_mfma_f32_16x16x32_bf16 v[34:37], v[242:245], v[194:197], v[34:37]
	v_mfma_f32_16x16x32_bf16 v[22:25], v[234:237], v[202:205], v[22:25]
	v_mfma_f32_16x16x32_bf16 v[18:21], v[242:245], v[202:205], v[18:21]
	v_mfma_f32_16x16x32_bf16 v[6:9], v[234:237], v[216:219], v[6:9]
	v_mfma_f32_16x16x32_bf16 v[2:5], v[242:245], v[216:219], v[2:5]
	v_mfma_f32_16x16x32_bf16 v[54:57], v[238:241], v[190:193], v[54:57]
	v_mfma_f32_16x16x32_bf16 v[50:53], v[246:249], v[190:193], v[50:53]
	v_mfma_f32_16x16x32_bf16 v[38:41], v[238:241], v[198:201], v[38:41]
	v_mfma_f32_16x16x32_bf16 v[34:37], v[246:249], v[198:201], v[34:37]
	v_mfma_f32_16x16x32_bf16 v[22:25], v[238:241], v[206:209], v[22:25]
	v_mfma_f32_16x16x32_bf16 v[18:21], v[246:249], v[206:209], v[18:21]
	v_mfma_f32_16x16x32_bf16 v[6:9], v[238:241], v[230:233], v[6:9]
	v_mfma_f32_16x16x32_bf16 v[2:5], v[246:249], v[230:233], v[2:5]
	s_setprio 0
	s_add_i32 s44, s44, 2
	s_add_u32 s28, s28, 0x100
	s_addc_u32 s29, s29, 0
	s_add_u32 s25, s25, 0x100
	s_addc_u32 s34, s34, 0
	s_cmp_gt_u32 s44, 13
	s_barrier
.LBB0_362:
	s_add_u32 s1, s28, 0xfffc0080
	s_addc_u32 s22, s29, -1
	s_add_i32 s23, 0, 0x10000
	v_add_u32_e32 v158, s23, v181
	ds_read_b128 v[130:133], v158
	ds_read_b128 v[134:137], v158 offset:1024
	ds_read_b128 v[154:157], v158 offset:2048
	ds_read_b128 v[186:189], v158 offset:3072
	s_cmp_eq_u32 s44, 12
	s_cselect_b32 s43, s17, s22
	s_cselect_b32 s42, s20, s1
	s_cselect_b32 s31, s9, s34
	s_cselect_b32 s30, s21, s25
	v_lshl_add_u64 v[160:161], s[28:29], 0, v[150:151]
	s_add_i32 m0, s49, 0xc000
	ds_read_b128 v[190:193], v185
	ds_read_b128 v[194:197], v185 offset:1024
	ds_read_b128 v[198:201], v185 offset:2048
	ds_read_b128 v[202:205], v185 offset:3072
	ds_read_b128 v[206:209], v185 offset:4096
	ds_read_b128 v[216:219], v185 offset:5120
	ds_read_b128 v[230:233], v185 offset:6144
	ds_read_b128 v[234:237], v185 offset:7168
	global_load_lds_dwordx4 v[160:161], off
	v_lshl_add_u64 v[160:161], s[28:29], 0, v[152:153]
	s_add_i32 m0, s49, 0xe000
	s_nop 0
	global_load_lds_dwordx4 v[160:161], off
	s_add_i32 s1, 0, 0x14000
	v_add_u32_e32 v158, s1, v181
	ds_read_b128 v[238:241], v158
	ds_read_b128 v[242:245], v158 offset:1024
	ds_read_b128 v[246:249], v158 offset:2048
	ds_read_b128 v[176:179], v158 offset:3072
	s_waitcnt vmcnt(8)
	s_waitcnt lgkmcnt(0)
	s_barrier
	s_setprio 1
	v_mfma_f32_16x16x32_bf16 v[126:129], v[130:133], v[190:193], v[126:129]
	v_mfma_f32_16x16x32_bf16 v[122:125], v[154:157], v[190:193], v[122:125]
	v_mfma_f32_16x16x32_bf16 v[110:113], v[130:133], v[198:201], v[110:113]
	v_mfma_f32_16x16x32_bf16 v[106:109], v[154:157], v[198:201], v[106:109]
	v_mfma_f32_16x16x32_bf16 v[94:97], v[130:133], v[206:209], v[94:97]
	v_mfma_f32_16x16x32_bf16 v[90:93], v[154:157], v[206:209], v[90:93]
	v_mfma_f32_16x16x32_bf16 v[78:81], v[130:133], v[230:233], v[78:81]
	v_mfma_f32_16x16x32_bf16 v[74:77], v[154:157], v[230:233], v[74:77]
	v_mfma_f32_16x16x32_bf16 v[126:129], v[134:137], v[194:197], v[126:129]
	v_mfma_f32_16x16x32_bf16 v[122:125], v[186:189], v[194:197], v[122:125]
	v_mfma_f32_16x16x32_bf16 v[110:113], v[134:137], v[202:205], v[110:113]
	v_mfma_f32_16x16x32_bf16 v[106:109], v[186:189], v[202:205], v[106:109]
	v_mfma_f32_16x16x32_bf16 v[94:97], v[134:137], v[216:219], v[94:97]
	v_mfma_f32_16x16x32_bf16 v[90:93], v[186:189], v[216:219], v[90:93]
	v_mfma_f32_16x16x32_bf16 v[78:81], v[134:137], v[234:237], v[78:81]
	v_mfma_f32_16x16x32_bf16 v[74:77], v[186:189], v[234:237], v[74:77]
	v_mfma_f32_16x16x32_bf16 v[118:121], v[238:241], v[190:193], v[118:121]
	v_mfma_f32_16x16x32_bf16 v[114:117], v[246:249], v[190:193], v[114:117]
	v_mfma_f32_16x16x32_bf16 v[102:105], v[238:241], v[198:201], v[102:105]
	v_mfma_f32_16x16x32_bf16 v[98:101], v[246:249], v[198:201], v[98:101]
	v_mfma_f32_16x16x32_bf16 v[86:89], v[238:241], v[206:209], v[86:89]
	v_mfma_f32_16x16x32_bf16 v[82:85], v[246:249], v[206:209], v[82:85]
	v_mfma_f32_16x16x32_bf16 v[70:73], v[238:241], v[230:233], v[70:73]
	v_mfma_f32_16x16x32_bf16 v[66:69], v[246:249], v[230:233], v[66:69]
	v_mfma_f32_16x16x32_bf16 v[118:121], v[242:245], v[194:197], v[118:121]
	v_mfma_f32_16x16x32_bf16 v[114:117], v[176:179], v[194:197], v[114:117]
	v_mfma_f32_16x16x32_bf16 v[102:105], v[242:245], v[202:205], v[102:105]
	v_mfma_f32_16x16x32_bf16 v[98:101], v[176:179], v[202:205], v[98:101]
	v_mfma_f32_16x16x32_bf16 v[86:89], v[242:245], v[216:219], v[86:89]
	v_mfma_f32_16x16x32_bf16 v[82:85], v[176:179], v[216:219], v[82:85]
	v_mfma_f32_16x16x32_bf16 v[70:73], v[242:245], v[234:237], v[70:73]
	v_mfma_f32_16x16x32_bf16 v[66:69], v[176:179], v[234:237], v[66:69]
	s_setprio 0
	s_barrier
	ds_read_b128 v[190:193], v185 offset:16384
	ds_read_b128 v[194:197], v185 offset:17408
	ds_read_b128 v[198:201], v185 offset:18432
	ds_read_b128 v[202:205], v185 offset:19456
	ds_read_b128 v[206:209], v185 offset:20480
	ds_read_b128 v[216:219], v185 offset:21504
	ds_read_b128 v[230:233], v185 offset:22528
	ds_read_b128 v[234:237], v185 offset:23552
	s_add_i32 s22, s23, s48
	v_lshl_add_u64 v[160:161], s[30:31], 0, v[0:1]
	s_mov_b32 m0, s22
	s_nop 0
	global_load_lds_dwordx4 v[160:161], off
	v_lshl_add_u64 v[220:221], s[30:31], 0, v[138:139]
	s_add_i32 m0, s22, 0x2000
	s_nop 0
	global_load_lds_dwordx4 v[220:221], off
	s_mov_b32 m0, s49
	v_lshl_add_u64 v[250:251], s[42:43], 0, v[142:143]
	global_load_lds_dwordx4 v[250:251], off
	v_lshl_add_u64 v[168:169], s[42:43], 0, v[140:141]
	s_mov_b32 m0, s50
	s_nop 0
	global_load_lds_dwordx4 v[168:169], off
	s_add_u32 s22, s30, 0x40000
	s_addc_u32 s23, s31, 0
	s_add_i32 s1, s1, s48
	s_mov_b32 m0, s1
	s_nop 0
	global_load_lds_dwordx4 v0, s[22:23]
	s_add_i32 m0, s1, 0x2000
	s_nop 0
	global_load_lds_dwordx4 v138, s[22:23]
	s_waitcnt vmcnt(8)
	s_waitcnt lgkmcnt(0)
	s_barrier
	s_setprio 1
	v_mfma_f32_16x16x32_bf16 v[62:65], v[130:133], v[190:193], v[62:65]
	v_mfma_f32_16x16x32_bf16 v[58:61], v[154:157], v[190:193], v[58:61]
	v_mfma_f32_16x16x32_bf16 v[46:49], v[130:133], v[198:201], v[46:49]
	v_mfma_f32_16x16x32_bf16 v[42:45], v[154:157], v[198:201], v[42:45]
	v_mfma_f32_16x16x32_bf16 v[30:33], v[130:133], v[206:209], v[30:33]
	v_mfma_f32_16x16x32_bf16 v[26:29], v[154:157], v[206:209], v[26:29]
	v_mfma_f32_16x16x32_bf16 v[14:17], v[130:133], v[230:233], v[14:17]
	v_mfma_f32_16x16x32_bf16 v[10:13], v[154:157], v[230:233], v[10:13]
	v_mfma_f32_16x16x32_bf16 v[62:65], v[134:137], v[194:197], v[62:65]
	v_mfma_f32_16x16x32_bf16 v[58:61], v[186:189], v[194:197], v[58:61]
	v_mfma_f32_16x16x32_bf16 v[46:49], v[134:137], v[202:205], v[46:49]
	v_mfma_f32_16x16x32_bf16 v[42:45], v[186:189], v[202:205], v[42:45]
	v_mfma_f32_16x16x32_bf16 v[30:33], v[134:137], v[216:219], v[30:33]
	v_mfma_f32_16x16x32_bf16 v[26:29], v[186:189], v[216:219], v[26:29]
	v_mfma_f32_16x16x32_bf16 v[14:17], v[134:137], v[234:237], v[14:17]
	v_mfma_f32_16x16x32_bf16 v[10:13], v[186:189], v[234:237], v[10:13]
	v_mfma_f32_16x16x32_bf16 v[54:57], v[238:241], v[190:193], v[54:57]
	v_mfma_f32_16x16x32_bf16 v[50:53], v[246:249], v[190:193], v[50:53]
	v_mfma_f32_16x16x32_bf16 v[38:41], v[238:241], v[198:201], v[38:41]
	v_mfma_f32_16x16x32_bf16 v[34:37], v[246:249], v[198:201], v[34:37]
	v_mfma_f32_16x16x32_bf16 v[22:25], v[238:241], v[206:209], v[22:25]
	v_mfma_f32_16x16x32_bf16 v[18:21], v[246:249], v[206:209], v[18:21]
	v_mfma_f32_16x16x32_bf16 v[6:9], v[238:241], v[230:233], v[6:9]
	v_mfma_f32_16x16x32_bf16 v[2:5], v[246:249], v[230:233], v[2:5]
	v_mfma_f32_16x16x32_bf16 v[54:57], v[242:245], v[194:197], v[54:57]
	v_mfma_f32_16x16x32_bf16 v[50:53], v[176:179], v[194:197], v[50:53]
	v_mfma_f32_16x16x32_bf16 v[38:41], v[242:245], v[202:205], v[38:41]
	v_mfma_f32_16x16x32_bf16 v[34:37], v[176:179], v[202:205], v[34:37]
	v_mfma_f32_16x16x32_bf16 v[22:25], v[242:245], v[216:219], v[22:25]
	v_mfma_f32_16x16x32_bf16 v[18:21], v[176:179], v[216:219], v[18:21]
	v_mfma_f32_16x16x32_bf16 v[6:9], v[242:245], v[234:237], v[6:9]
	v_mfma_f32_16x16x32_bf16 v[2:5], v[176:179], v[234:237], v[2:5]
	s_setprio 0
	s_barrier
	s_add_i32 s1, 0, 0x18000
	v_add_u32_e32 v158, s1, v181
	ds_read_b128 v[130:133], v158
	ds_read_b128 v[134:137], v158 offset:1024
	ds_read_b128 v[154:157], v158 offset:2048
	ds_read_b128 v[176:179], v158 offset:3072
	s_add_u32 s22, s42, 0x40000
	s_addc_u32 s23, s43, 0
	s_mov_b32 m0, s51
	v_lshl_add_u64 v[234:235], s[22:23], 0, v[142:143]
	ds_read_b128 v[186:189], v185 offset:32768
	ds_read_b128 v[190:193], v185 offset:33792
	ds_read_b128 v[194:197], v185 offset:34816
	ds_read_b128 v[198:201], v185 offset:35840
	ds_read_b128 v[202:205], v185 offset:36864
	ds_read_b128 v[206:209], v185 offset:37888
	ds_read_b128 v[216:219], v185 offset:38912
	ds_read_b128 v[230:233], v185 offset:39936
	global_load_lds_dwordx4 v[234:235], off
	v_lshl_add_u64 v[234:235], s[22:23], 0, v[140:141]
	s_mov_b32 m0, s52
	s_nop 0
	global_load_lds_dwordx4 v[234:235], off
	s_add_i32 s33, 0, 0x1c000
	v_add_u32_e32 v158, s33, v181
	ds_read_b128 v[234:237], v158
	ds_read_b128 v[238:241], v158 offset:1024
	ds_read_b128 v[242:245], v158 offset:2048
	ds_read_b128 v[246:249], v158 offset:3072
	s_waitcnt vmcnt(8)
	s_waitcnt lgkmcnt(0)
	s_barrier
	s_setprio 1
	v_mfma_f32_16x16x32_bf16 v[126:129], v[130:133], v[186:189], v[126:129]
	v_mfma_f32_16x16x32_bf16 v[122:125], v[154:157], v[186:189], v[122:125]
	v_mfma_f32_16x16x32_bf16 v[110:113], v[130:133], v[194:197], v[110:113]
	v_mfma_f32_16x16x32_bf16 v[106:109], v[154:157], v[194:197], v[106:109]
	v_mfma_f32_16x16x32_bf16 v[94:97], v[130:133], v[202:205], v[94:97]
	v_mfma_f32_16x16x32_bf16 v[90:93], v[154:157], v[202:205], v[90:93]
	v_mfma_f32_16x16x32_bf16 v[78:81], v[130:133], v[216:219], v[78:81]
	v_mfma_f32_16x16x32_bf16 v[74:77], v[154:157], v[216:219], v[74:77]
	v_mfma_f32_16x16x32_bf16 v[126:129], v[134:137], v[190:193], v[126:129]
	v_mfma_f32_16x16x32_bf16 v[122:125], v[176:179], v[190:193], v[122:125]
	v_mfma_f32_16x16x32_bf16 v[110:113], v[134:137], v[198:201], v[110:113]
	v_mfma_f32_16x16x32_bf16 v[106:109], v[176:179], v[198:201], v[106:109]
	v_mfma_f32_16x16x32_bf16 v[94:97], v[134:137], v[206:209], v[94:97]
	v_mfma_f32_16x16x32_bf16 v[90:93], v[176:179], v[206:209], v[90:93]
	v_mfma_f32_16x16x32_bf16 v[78:81], v[134:137], v[230:233], v[78:81]
	v_mfma_f32_16x16x32_bf16 v[74:77], v[176:179], v[230:233], v[74:77]
	v_mfma_f32_16x16x32_bf16 v[118:121], v[234:237], v[186:189], v[118:121]
	v_mfma_f32_16x16x32_bf16 v[114:117], v[242:245], v[186:189], v[114:117]
	v_mfma_f32_16x16x32_bf16 v[102:105], v[234:237], v[194:197], v[102:105]
	v_mfma_f32_16x16x32_bf16 v[98:101], v[242:245], v[194:197], v[98:101]
	v_mfma_f32_16x16x32_bf16 v[86:89], v[234:237], v[202:205], v[86:89]
	v_mfma_f32_16x16x32_bf16 v[82:85], v[242:245], v[202:205], v[82:85]
	v_mfma_f32_16x16x32_bf16 v[70:73], v[234:237], v[216:219], v[70:73]
	v_mfma_f32_16x16x32_bf16 v[66:69], v[242:245], v[216:219], v[66:69]
	v_mfma_f32_16x16x32_bf16 v[118:121], v[238:241], v[190:193], v[118:121]
	v_mfma_f32_16x16x32_bf16 v[114:117], v[246:249], v[190:193], v[114:117]
	v_mfma_f32_16x16x32_bf16 v[102:105], v[238:241], v[198:201], v[102:105]
	v_mfma_f32_16x16x32_bf16 v[98:101], v[246:249], v[198:201], v[98:101]
	v_mfma_f32_16x16x32_bf16 v[86:89], v[238:241], v[206:209], v[86:89]
	v_mfma_f32_16x16x32_bf16 v[82:85], v[246:249], v[206:209], v[82:85]
	v_mfma_f32_16x16x32_bf16 v[70:73], v[238:241], v[230:233], v[70:73]
	v_mfma_f32_16x16x32_bf16 v[66:69], v[246:249], v[230:233], v[66:69]
	s_setprio 0
	s_barrier
	ds_read_b128 v[186:189], v185 offset:49152
	ds_read_b128 v[190:193], v185 offset:50176
	ds_read_b128 v[194:197], v185 offset:51200
	ds_read_b128 v[198:201], v185 offset:52224
	ds_read_b128 v[202:205], v185 offset:53248
	ds_read_b128 v[206:209], v185 offset:54272
	ds_read_b128 v[216:219], v185 offset:55296
	ds_read_b128 v[230:233], v185 offset:56320
	s_add_i32 s1, s1, s48
	v_lshl_add_u64 v[160:161], v[160:161], 0, s[12:13]
	s_mov_b32 m0, s1
	s_nop 0
	global_load_lds_dwordx4 v[160:161], off
	v_lshl_add_u64 v[160:161], v[220:221], 0, s[12:13]
	s_add_i32 m0, s1, 0x2000
	s_nop 0
	global_load_lds_dwordx4 v[160:161], off
	s_mov_b32 m0, s55
	v_lshl_add_u64 v[160:161], v[250:251], 0, s[12:13]
	global_load_lds_dwordx4 v[160:161], off
	v_lshl_add_u64 v[160:161], v[168:169], 0, s[12:13]
	s_mov_b32 m0, s56
	s_nop 0
	global_load_lds_dwordx4 v[160:161], off
	s_add_u32 s22, s30, 0x40080
	s_addc_u32 s23, s31, 0
	s_add_i32 s1, s33, s48
	s_mov_b32 m0, s1
	s_nop 0
	global_load_lds_dwordx4 v0, s[22:23]
	s_add_i32 m0, s1, 0x2000
	s_nop 0
	global_load_lds_dwordx4 v138, s[22:23]
	s_waitcnt vmcnt(8)
	s_waitcnt lgkmcnt(0)
	s_barrier
	s_setprio 1
	v_mfma_f32_16x16x32_bf16 v[62:65], v[130:133], v[186:189], v[62:65]
	v_mfma_f32_16x16x32_bf16 v[58:61], v[154:157], v[186:189], v[58:61]
	v_mfma_f32_16x16x32_bf16 v[46:49], v[130:133], v[194:197], v[46:49]
	v_mfma_f32_16x16x32_bf16 v[42:45], v[154:157], v[194:197], v[42:45]
	v_mfma_f32_16x16x32_bf16 v[30:33], v[130:133], v[202:205], v[30:33]
	v_mfma_f32_16x16x32_bf16 v[26:29], v[154:157], v[202:205], v[26:29]
	v_mfma_f32_16x16x32_bf16 v[14:17], v[130:133], v[216:219], v[14:17]
	v_mfma_f32_16x16x32_bf16 v[10:13], v[154:157], v[216:219], v[10:13]
	v_mfma_f32_16x16x32_bf16 v[62:65], v[134:137], v[190:193], v[62:65]
	v_mfma_f32_16x16x32_bf16 v[58:61], v[176:179], v[190:193], v[58:61]
	v_mfma_f32_16x16x32_bf16 v[46:49], v[134:137], v[198:201], v[46:49]
	v_mfma_f32_16x16x32_bf16 v[42:45], v[176:179], v[198:201], v[42:45]
	v_mfma_f32_16x16x32_bf16 v[30:33], v[134:137], v[206:209], v[30:33]
	v_mfma_f32_16x16x32_bf16 v[26:29], v[176:179], v[206:209], v[26:29]
	v_mfma_f32_16x16x32_bf16 v[14:17], v[134:137], v[230:233], v[14:17]
	v_mfma_f32_16x16x32_bf16 v[10:13], v[176:179], v[230:233], v[10:13]
	v_mfma_f32_16x16x32_bf16 v[54:57], v[234:237], v[186:189], v[54:57]
	v_mfma_f32_16x16x32_bf16 v[50:53], v[242:245], v[186:189], v[50:53]
	v_mfma_f32_16x16x32_bf16 v[38:41], v[234:237], v[194:197], v[38:41]
	v_mfma_f32_16x16x32_bf16 v[34:37], v[242:245], v[194:197], v[34:37]
	v_mfma_f32_16x16x32_bf16 v[22:25], v[234:237], v[202:205], v[22:25]
	v_mfma_f32_16x16x32_bf16 v[18:21], v[242:245], v[202:205], v[18:21]
	v_mfma_f32_16x16x32_bf16 v[6:9], v[234:237], v[216:219], v[6:9]
	v_mfma_f32_16x16x32_bf16 v[2:5], v[242:245], v[216:219], v[2:5]
	v_mfma_f32_16x16x32_bf16 v[54:57], v[238:241], v[190:193], v[54:57]
	v_mfma_f32_16x16x32_bf16 v[50:53], v[246:249], v[190:193], v[50:53]
	v_mfma_f32_16x16x32_bf16 v[38:41], v[238:241], v[198:201], v[38:41]
	v_mfma_f32_16x16x32_bf16 v[34:37], v[246:249], v[198:201], v[34:37]
	v_mfma_f32_16x16x32_bf16 v[22:25], v[238:241], v[206:209], v[22:25]
	v_mfma_f32_16x16x32_bf16 v[18:21], v[246:249], v[206:209], v[18:21]
	v_mfma_f32_16x16x32_bf16 v[6:9], v[238:241], v[230:233], v[6:9]
	v_mfma_f32_16x16x32_bf16 v[2:5], v[246:249], v[230:233], v[2:5]
	s_setprio 0
	s_add_i32 s44, s44, 2
	s_add_u32 s28, s28, 0x100
	s_addc_u32 s29, s29, 0
	s_add_u32 s25, s25, 0x100
	s_addc_u32 s34, s34, 0
	s_cmp_gt_u32 s44, 13
	s_barrier
	s_cbranch_scc0 .LBB0_362
	s_cmpk_gt_u32 s4, 0xff
	s_cbranch_scc1 .Lrs_proj1_post
	s_barrier
